# P2 and P8 GEMM epilogues: the per-row rstd values are loaded once up front (8 loads, one wait) instead of a load + vmcnt(0) before every row group
# speedup vs baseline: 1.0130x; 1.0002x over previous
; DEV unsigned cvtpk(float lo, float hi) { f32x2 v = {lo, hi}; bf16x2_t b = __builtin_convertvector(v, bf16x2_t); return __builtin_bit_cast(unsigned, b); }
; DEV float sigm(float x) { return __builtin_amdgcn_rcpf(1.f + __expf(-x)); }
;   __device__ __forceinline__ void operator()(const pg8::f32x4 (&acc)[2][2][4][2], const pg8::Unit& u, int wr, int wc, int fr, int fq) const {
; #pragma unroll
;     for (int ai = 0; ai < 2; ++ai)
; #pragma unroll
;       for (int m = 0; m < 4; ++m) {
;         const int row = u.pm * 256 + ai * 128 + wr * 64 + m * 16 + fr; const float rs = RS[row];
;         bf16_t* rp = TT + (size_t)row * DFF + u.pn * 128 + wc * 32 + 4 * fq;
; #pragma unroll
;         for (int n = 0; n < 2; ++n) {
;           const pg8::f32x4 g = acc[ai][0][m][n] * rs, uu = acc[ai][1][m][n] * rs;
;           u32x2 w; w[0] = cvtpk(g[0] * sigm(g[0]) * uu[0], g[1] * sigm(g[1]) * uu[1]); w[1] = cvtpk(g[2] * sigm(g[2]) * uu[2], g[3] * sigm(g[3]) * uu[3]);
;           *(u32x2*)(rp + n * 16) = w;
;         }
;       }
;   }
.LBB0_393:
	v_lshl_add_u32 v138, s80, 8, v140
	v_mov_b32_e32 v158, v138
	v_ashrrev_i32_e32 v159, 31, v158
	v_lshl_add_u64 v[160:161], v[158:159], 2, s[14:15]
	global_load_dword v150, v[160:161], off
	v_add_u32_e32 v158, 16, v138
	v_ashrrev_i32_e32 v159, 31, v158
	v_lshl_add_u64 v[160:161], v[158:159], 2, s[14:15]
	global_load_dword v151, v[160:161], off
	v_add_u32_e32 v158, 32, v138
	v_ashrrev_i32_e32 v159, 31, v158
	v_lshl_add_u64 v[160:161], v[158:159], 2, s[14:15]
	global_load_dword v152, v[160:161], off
	v_add_u32_e32 v158, 48, v138
	v_ashrrev_i32_e32 v159, 31, v158
	v_lshl_add_u64 v[160:161], v[158:159], 2, s[14:15]
	global_load_dword v153, v[160:161], off
	v_add_u32_e32 v158, 128, v138
	v_ashrrev_i32_e32 v159, 31, v158
	v_lshl_add_u64 v[160:161], v[158:159], 2, s[14:15]
	global_load_dword v154, v[160:161], off
	v_add_u32_e32 v158, 144, v138
	v_ashrrev_i32_e32 v159, 31, v158
	v_lshl_add_u64 v[160:161], v[158:159], 2, s[14:15]
	global_load_dword v155, v[160:161], off
	v_add_u32_e32 v158, 160, v138
	v_ashrrev_i32_e32 v159, 31, v158
	v_lshl_add_u64 v[160:161], v[158:159], 2, s[14:15]
	global_load_dword v156, v[160:161], off
	v_add_u32_e32 v158, 176, v138
	v_ashrrev_i32_e32 v159, 31, v158
	v_lshl_add_u64 v[160:161], v[158:159], 2, s[14:15]
	global_load_dword v157, v[160:161], off
	s_waitcnt vmcnt(0)
	v_ashrrev_i32_e32 v139, 31, v138
	v_lshl_add_u64 v[136:137], v[138:139], 2, s[14:15]
	v_mov_b32_e32 v144, v150
	s_lshl_b32 s24, s39, 7
	v_mov_b64_e32 v[136:137], s[16:17]
	s_movk_i32 s4, 0x1600
	s_ashr_i32 s25, s24, 31
	v_mad_i64_i32 v[146:147], s[26:27], v138, s4, v[136:137]
	s_lshl_b64 s[26:27], s[24:25], 1
	s_nop 0
	v_lshl_add_u64 v[146:147], v[146:147], 0, s[26:27]
	v_lshl_add_u64 v[146:147], v[146:147], 0, s[54:55]
	v_lshl_add_u64 v[146:147], v[146:147], 0, v[196:197]
	s_andn2_b64 vcc, exec, s[40:41]
	v_pk_mul_f32 v[124:125], v[124:125], v[144:145] op_sel_hi:[1,0]
	s_nop 0
	v_mul_f32_e32 v139, 0xbfb8aa3b, v124
	v_exp_f32_e32 v139, v139
	v_pk_mul_f32 v[116:117], v[116:117], v[144:145] op_sel_hi:[1,0]
	v_pk_mul_f32 v[126:127], v[126:127], v[144:145] op_sel_hi:[1,0]
	v_pk_mul_f32 v[118:119], v[118:119], v[144:145] op_sel_hi:[1,0]
	v_add_f32_e32 v139, 1.0, v139
	v_rcp_f32_e32 v148, v139
	v_mul_f32_e32 v139, 0xbfb8aa3b, v125
	v_exp_f32_e32 v139, v139
	v_pk_mul_f32 v[112:113], v[112:113], v[144:145] op_sel_hi:[1,0]
	v_pk_mul_f32 v[114:115], v[114:115], v[144:145] op_sel_hi:[1,0]
	v_add_f32_e32 v139, 1.0, v139
	v_rcp_f32_e32 v149, v139
	s_nop 0
	v_pk_mul_f32 v[124:125], v[124:125], v[148:149]
	s_nop 0
	v_pk_mul_f32 v[116:117], v[116:117], v[124:125]
	s_nop 0
	v_cvt_pk_bf16_f32 v116, v116, v117
	v_mul_f32_e32 v117, 0xbfb8aa3b, v126
	v_exp_f32_e32 v117, v117
	s_nop 0
	v_add_f32_e32 v117, 1.0, v117
	v_rcp_f32_e32 v124, v117
	v_mul_f32_e32 v117, 0xbfb8aa3b, v127
	v_exp_f32_e32 v117, v117
	s_nop 0
	v_add_f32_e32 v117, 1.0, v117
	v_rcp_f32_e32 v125, v117
	s_nop 0
	v_pk_mul_f32 v[124:125], v[126:127], v[124:125]
	s_nop 0
	v_pk_mul_f32 v[118:119], v[118:119], v[124:125]
	s_nop 0
	v_cvt_pk_bf16_f32 v117, v118, v119
	v_pk_mul_f32 v[118:119], v[120:121], v[144:145] op_sel_hi:[1,0]
	global_store_dwordx2 v[146:147], v[116:117], off
	v_mul_f32_e32 v120, 0xbfb8aa3b, v118
	v_mul_f32_e32 v121, 0xbfb8aa3b, v119
	v_exp_f32_e32 v120, v120
	v_exp_f32_e32 v121, v121
	v_pk_mul_f32 v[116:117], v[122:123], v[144:145] op_sel_hi:[1,0]
	v_add_f32_e32 v120, 1.0, v120
	v_add_f32_e32 v121, 1.0, v121
	v_rcp_f32_e32 v120, v120
	v_rcp_f32_e32 v121, v121
	s_nop 0
	v_pk_mul_f32 v[118:119], v[118:119], v[120:121]
	s_nop 0
	v_pk_mul_f32 v[112:113], v[112:113], v[118:119]
	s_nop 0
	v_cvt_pk_bf16_f32 v112, v112, v113
	v_mul_f32_e32 v113, 0xbfb8aa3b, v116
	v_exp_f32_e32 v113, v113
	s_nop 0
	v_add_f32_e32 v113, 1.0, v113
	v_rcp_f32_e32 v118, v113
	v_mul_f32_e32 v113, 0xbfb8aa3b, v117
	v_exp_f32_e32 v113, v113
	s_nop 0
	v_add_f32_e32 v113, 1.0, v113
	v_rcp_f32_e32 v119, v113
	s_nop 0
	v_pk_mul_f32 v[116:117], v[116:117], v[118:119]
	s_nop 0
	v_pk_mul_f32 v[114:115], v[114:115], v[116:117]
	s_nop 0
	v_cvt_pk_bf16_f32 v113, v114, v115
	global_store_dwordx2 v[146:147], v[112:113], off offset:32
	v_or_b32_e32 v112, 16, v138
	v_ashrrev_i32_e32 v113, 31, v112
	v_lshl_add_u64 v[114:115], v[112:113], 2, s[14:15]
	v_mov_b32_e32 v114, v151
	v_mad_i64_i32 v[112:113], s[24:25], v112, s4, v[136:137]
	v_lshl_add_u64 v[112:113], v[112:113], 0, s[26:27]
	v_lshl_add_u64 v[112:113], v[112:113], 0, s[54:55]
	v_lshl_add_u64 v[112:113], v[112:113], 0, v[196:197]
	v_pk_mul_f32 v[108:109], v[108:109], v[114:115] op_sel_hi:[1,0]
	v_pk_mul_f32 v[110:111], v[110:111], v[114:115] op_sel_hi:[1,0]
	v_pk_mul_f32 v[102:103], v[102:103], v[114:115] op_sel_hi:[1,0]
	v_pk_mul_f32 v[100:101], v[100:101], v[114:115] op_sel_hi:[1,0]
	v_mul_f32_e32 v115, 0xbfb8aa3b, v108
	v_exp_f32_e32 v115, v115
	s_nop 0
	v_add_f32_e32 v115, 1.0, v115
	v_rcp_f32_e32 v116, v115
	v_mul_f32_e32 v115, 0xbfb8aa3b, v109
	v_exp_f32_e32 v115, v115
	s_nop 0
	v_add_f32_e32 v115, 1.0, v115
	v_rcp_f32_e32 v117, v115
	v_pk_mul_f32 v[96:97], v[96:97], v[114:115] op_sel_hi:[1,0]
	v_pk_mul_f32 v[98:99], v[98:99], v[114:115] op_sel_hi:[1,0]
	v_pk_mul_f32 v[108:109], v[108:109], v[116:117]
	s_nop 0
	v_pk_mul_f32 v[100:101], v[100:101], v[108:109]
	s_nop 0
	v_cvt_pk_bf16_f32 v100, v100, v101
	v_mul_f32_e32 v101, 0xbfb8aa3b, v110
	v_exp_f32_e32 v101, v101
	s_nop 0
	v_add_f32_e32 v101, 1.0, v101
	v_rcp_f32_e32 v108, v101
	v_mul_f32_e32 v101, 0xbfb8aa3b, v111
	v_exp_f32_e32 v101, v101
	s_nop 0
	v_add_f32_e32 v101, 1.0, v101
	v_rcp_f32_e32 v109, v101
	s_nop 0
	v_pk_mul_f32 v[108:109], v[110:111], v[108:109]
	s_nop 0
	v_pk_mul_f32 v[102:103], v[102:103], v[108:109]
; DEV unsigned cvtpk(float lo, float hi) { f32x2 v = {lo, hi}; bf16x2_t b = __builtin_convertvector(v, bf16x2_t); return __builtin_bit_cast(unsigned, b); }
; DEV float sigm(float x) { return __builtin_amdgcn_rcpf(1.f + __expf(-x)); }
;   __device__ __forceinline__ void operator()(const pg8::f32x4 (&acc)[2][2][4][2], const pg8::Unit& u, int wr, int wc, int fr, int fq) const {
; #pragma unroll
;     for (int ai = 0; ai < 2; ++ai)
; #pragma unroll
;       for (int m = 0; m < 4; ++m) {
;         const int row = u.pm * 256 + ai * 128 + wr * 64 + m * 16 + fr; const float rs = RS[row];
;         bf16_t* rp = TT + (size_t)row * DFF + u.pn * 128 + wc * 32 + 4 * fq;
; #pragma unroll
;         for (int n = 0; n < 2; ++n) {
;           const pg8::f32x4 g = acc[ai][0][m][n] * rs, uu = acc[ai][1][m][n] * rs;
;           u32x2 w; w[0] = cvtpk(g[0] * sigm(g[0]) * uu[0], g[1] * sigm(g[1]) * uu[1]); w[1] = cvtpk(g[2] * sigm(g[2]) * uu[2], g[3] * sigm(g[3]) * uu[3]);
;           *(u32x2*)(rp + n * 16) = w;
;         }
;       }
;   }
	s_nop 0
	v_cvt_pk_bf16_f32 v101, v102, v103
	v_pk_mul_f32 v[102:103], v[104:105], v[114:115] op_sel_hi:[1,0]
	global_store_dwordx2 v[112:113], v[100:101], off
	v_mul_f32_e32 v104, 0xbfb8aa3b, v102
	v_mul_f32_e32 v105, 0xbfb8aa3b, v103
	v_exp_f32_e32 v104, v104
	v_exp_f32_e32 v105, v105
	v_pk_mul_f32 v[100:101], v[106:107], v[114:115] op_sel_hi:[1,0]
	v_add_f32_e32 v104, 1.0, v104
	v_add_f32_e32 v105, 1.0, v105
	v_rcp_f32_e32 v104, v104
	v_rcp_f32_e32 v105, v105
	s_nop 0
	v_pk_mul_f32 v[102:103], v[102:103], v[104:105]
	s_nop 0
	v_pk_mul_f32 v[96:97], v[96:97], v[102:103]
	s_nop 0
	v_cvt_pk_bf16_f32 v96, v96, v97
	v_mul_f32_e32 v97, 0xbfb8aa3b, v100
	v_exp_f32_e32 v97, v97
	s_nop 0
	v_add_f32_e32 v97, 1.0, v97
	v_rcp_f32_e32 v102, v97
	v_mul_f32_e32 v97, 0xbfb8aa3b, v101
	v_exp_f32_e32 v97, v97
	s_nop 0
	v_add_f32_e32 v97, 1.0, v97
	v_rcp_f32_e32 v103, v97
	s_nop 0
	v_pk_mul_f32 v[100:101], v[100:101], v[102:103]
	s_nop 0
	v_pk_mul_f32 v[98:99], v[98:99], v[100:101]
	s_nop 0
	v_cvt_pk_bf16_f32 v97, v98, v99
	global_store_dwordx2 v[112:113], v[96:97], off offset:32
	v_or_b32_e32 v96, 32, v138
	v_ashrrev_i32_e32 v97, 31, v96
	v_lshl_add_u64 v[98:99], v[96:97], 2, s[14:15]
	v_mov_b32_e32 v98, v152
	v_mad_i64_i32 v[96:97], s[24:25], v96, s4, v[136:137]
	v_lshl_add_u64 v[96:97], v[96:97], 0, s[26:27]
	v_lshl_add_u64 v[96:97], v[96:97], 0, s[54:55]
	v_lshl_add_u64 v[96:97], v[96:97], 0, v[196:197]
	v_pk_mul_f32 v[92:93], v[92:93], v[98:99] op_sel_hi:[1,0]
	v_pk_mul_f32 v[94:95], v[94:95], v[98:99] op_sel_hi:[1,0]
	v_pk_mul_f32 v[86:87], v[86:87], v[98:99] op_sel_hi:[1,0]
	v_pk_mul_f32 v[84:85], v[84:85], v[98:99] op_sel_hi:[1,0]
	v_mul_f32_e32 v99, 0xbfb8aa3b, v92
	v_exp_f32_e32 v99, v99
	s_nop 0
	v_add_f32_e32 v99, 1.0, v99
	v_rcp_f32_e32 v100, v99
	v_mul_f32_e32 v99, 0xbfb8aa3b, v93
	v_exp_f32_e32 v99, v99
	s_nop 0
	v_add_f32_e32 v99, 1.0, v99
	v_rcp_f32_e32 v101, v99
	v_pk_mul_f32 v[80:81], v[80:81], v[98:99] op_sel_hi:[1,0]
	v_pk_mul_f32 v[82:83], v[82:83], v[98:99] op_sel_hi:[1,0]
	v_pk_mul_f32 v[92:93], v[92:93], v[100:101]
	s_nop 0
	v_pk_mul_f32 v[84:85], v[84:85], v[92:93]
	s_nop 0
	v_cvt_pk_bf16_f32 v84, v84, v85
	v_mul_f32_e32 v85, 0xbfb8aa3b, v94
	v_exp_f32_e32 v85, v85
	s_nop 0
	v_add_f32_e32 v85, 1.0, v85
	v_rcp_f32_e32 v92, v85
	v_mul_f32_e32 v85, 0xbfb8aa3b, v95
	v_exp_f32_e32 v85, v85
	s_nop 0
	v_add_f32_e32 v85, 1.0, v85
	v_rcp_f32_e32 v93, v85
	s_nop 0
	v_pk_mul_f32 v[92:93], v[94:95], v[92:93]
	s_nop 0
	v_pk_mul_f32 v[86:87], v[86:87], v[92:93]
	s_nop 0
	v_cvt_pk_bf16_f32 v85, v86, v87
	v_pk_mul_f32 v[86:87], v[88:89], v[98:99] op_sel_hi:[1,0]
	global_store_dwordx2 v[96:97], v[84:85], off
	v_mul_f32_e32 v88, 0xbfb8aa3b, v86
	v_mul_f32_e32 v89, 0xbfb8aa3b, v87
	v_exp_f32_e32 v88, v88
	v_exp_f32_e32 v89, v89
	v_pk_mul_f32 v[84:85], v[90:91], v[98:99] op_sel_hi:[1,0]
	v_add_f32_e32 v88, 1.0, v88
	v_add_f32_e32 v89, 1.0, v89
	v_rcp_f32_e32 v88, v88
	v_rcp_f32_e32 v89, v89
	s_nop 0
	v_pk_mul_f32 v[86:87], v[86:87], v[88:89]
	s_nop 0
	v_pk_mul_f32 v[80:81], v[80:81], v[86:87]
	s_nop 0
	v_cvt_pk_bf16_f32 v80, v80, v81
	v_mul_f32_e32 v81, 0xbfb8aa3b, v84
	v_exp_f32_e32 v81, v81
	s_nop 0
	v_add_f32_e32 v81, 1.0, v81
	v_rcp_f32_e32 v86, v81
	v_mul_f32_e32 v81, 0xbfb8aa3b, v85
	v_exp_f32_e32 v81, v81
	s_nop 0
	v_add_f32_e32 v81, 1.0, v81
	v_rcp_f32_e32 v87, v81
	s_nop 0
	v_pk_mul_f32 v[84:85], v[84:85], v[86:87]
	s_nop 0
	v_pk_mul_f32 v[82:83], v[82:83], v[84:85]
	s_nop 0
	v_cvt_pk_bf16_f32 v81, v82, v83
	global_store_dwordx2 v[96:97], v[80:81], off offset:32
	v_or_b32_e32 v80, 48, v138
	v_ashrrev_i32_e32 v81, 31, v80
	v_lshl_add_u64 v[82:83], v[80:81], 2, s[14:15]
	v_mov_b32_e32 v82, v153
	v_mad_i64_i32 v[80:81], s[24:25], v80, s4, v[136:137]
	v_lshl_add_u64 v[80:81], v[80:81], 0, s[26:27]
	v_lshl_add_u64 v[80:81], v[80:81], 0, s[54:55]
	v_lshl_add_u64 v[80:81], v[80:81], 0, v[196:197]
	v_pk_mul_f32 v[76:77], v[76:77], v[82:83] op_sel_hi:[1,0]
	v_pk_mul_f32 v[78:79], v[78:79], v[82:83] op_sel_hi:[1,0]
	v_pk_mul_f32 v[70:71], v[70:71], v[82:83] op_sel_hi:[1,0]
	v_pk_mul_f32 v[68:69], v[68:69], v[82:83] op_sel_hi:[1,0]
	v_mul_f32_e32 v83, 0xbfb8aa3b, v76
	v_exp_f32_e32 v83, v83
	s_nop 0
	v_add_f32_e32 v83, 1.0, v83
	v_rcp_f32_e32 v84, v83
	v_mul_f32_e32 v83, 0xbfb8aa3b, v77
	v_exp_f32_e32 v83, v83
	s_nop 0
	v_add_f32_e32 v83, 1.0, v83
	v_rcp_f32_e32 v85, v83
	v_pk_mul_f32 v[64:65], v[64:65], v[82:83] op_sel_hi:[1,0]
	v_pk_mul_f32 v[66:67], v[66:67], v[82:83] op_sel_hi:[1,0]
	v_pk_mul_f32 v[76:77], v[76:77], v[84:85]
	s_nop 0
	v_pk_mul_f32 v[68:69], v[68:69], v[76:77]
	s_nop 0
	v_cvt_pk_bf16_f32 v68, v68, v69
	v_mul_f32_e32 v69, 0xbfb8aa3b, v78
	v_exp_f32_e32 v69, v69
	s_nop 0
	v_add_f32_e32 v69, 1.0, v69
	v_rcp_f32_e32 v76, v69
	v_mul_f32_e32 v69, 0xbfb8aa3b, v79
	v_exp_f32_e32 v69, v69
	s_nop 0
	v_add_f32_e32 v69, 1.0, v69
	v_rcp_f32_e32 v77, v69
	s_nop 0
	v_pk_mul_f32 v[76:77], v[78:79], v[76:77]
	s_nop 0
	v_pk_mul_f32 v[70:71], v[70:71], v[76:77]
	s_nop 0
	v_cvt_pk_bf16_f32 v69, v70, v71
	v_pk_mul_f32 v[70:71], v[72:73], v[82:83] op_sel_hi:[1,0]
	global_store_dwordx2 v[80:81], v[68:69], off
	v_mul_f32_e32 v72, 0xbfb8aa3b, v70
	v_mul_f32_e32 v73, 0xbfb8aa3b, v71
	v_exp_f32_e32 v72, v72
	v_exp_f32_e32 v73, v73
	v_pk_mul_f32 v[68:69], v[74:75], v[82:83] op_sel_hi:[1,0]
	v_add_f32_e32 v72, 1.0, v72
	v_add_f32_e32 v73, 1.0, v73
	v_rcp_f32_e32 v72, v72
	v_rcp_f32_e32 v73, v73
	s_nop 0
	v_pk_mul_f32 v[70:71], v[70:71], v[72:73]
	s_nop 0
	v_pk_mul_f32 v[64:65], v[64:65], v[70:71]
	s_nop 0
	v_cvt_pk_bf16_f32 v64, v64, v65
	v_mul_f32_e32 v65, 0xbfb8aa3b, v68
	v_exp_f32_e32 v65, v65
	s_nop 0
	v_add_f32_e32 v65, 1.0, v65
	v_rcp_f32_e32 v70, v65
; DEV unsigned cvtpk(float lo, float hi) { f32x2 v = {lo, hi}; bf16x2_t b = __builtin_convertvector(v, bf16x2_t); return __builtin_bit_cast(unsigned, b); }
; DEV float sigm(float x) { return __builtin_amdgcn_rcpf(1.f + __expf(-x)); }
;   __device__ __forceinline__ void operator()(const pg8::f32x4 (&acc)[2][2][4][2], const pg8::Unit& u, int wr, int wc, int fr, int fq) const {
; #pragma unroll
;     for (int ai = 0; ai < 2; ++ai)
; #pragma unroll
;       for (int m = 0; m < 4; ++m) {
;         const int row = u.pm * 256 + ai * 128 + wr * 64 + m * 16 + fr; const float rs = RS[row];
;         bf16_t* rp = TT + (size_t)row * DFF + u.pn * 128 + wc * 32 + 4 * fq;
; #pragma unroll
;         for (int n = 0; n < 2; ++n) {
;           const pg8::f32x4 g = acc[ai][0][m][n] * rs, uu = acc[ai][1][m][n] * rs;
;           u32x2 w; w[0] = cvtpk(g[0] * sigm(g[0]) * uu[0], g[1] * sigm(g[1]) * uu[1]); w[1] = cvtpk(g[2] * sigm(g[2]) * uu[2], g[3] * sigm(g[3]) * uu[3]);
;           *(u32x2*)(rp + n * 16) = w;
;         }
;       }
;   }
	v_mul_f32_e32 v65, 0xbfb8aa3b, v69
	v_exp_f32_e32 v65, v65
	s_nop 0
	v_add_f32_e32 v65, 1.0, v65
	v_rcp_f32_e32 v71, v65
	s_nop 0
	v_pk_mul_f32 v[68:69], v[68:69], v[70:71]
	s_nop 0
	v_pk_mul_f32 v[66:67], v[66:67], v[68:69]
	s_nop 0
	v_cvt_pk_bf16_f32 v65, v66, v67
	global_store_dwordx2 v[80:81], v[64:65], off offset:32
	v_add_u32_e32 v64, 0x80, v138
	v_ashrrev_i32_e32 v65, 31, v64
	v_lshl_add_u64 v[66:67], v[64:65], 2, s[14:15]
	v_mov_b32_e32 v66, v154
	v_mad_i64_i32 v[64:65], s[24:25], v64, s4, v[136:137]
	v_lshl_add_u64 v[64:65], v[64:65], 0, s[26:27]
	v_lshl_add_u64 v[64:65], v[64:65], 0, s[54:55]
	v_lshl_add_u64 v[64:65], v[64:65], 0, v[196:197]
	v_pk_mul_f32 v[60:61], v[60:61], v[66:67] op_sel_hi:[1,0]
	v_pk_mul_f32 v[62:63], v[62:63], v[66:67] op_sel_hi:[1,0]
	v_pk_mul_f32 v[54:55], v[54:55], v[66:67] op_sel_hi:[1,0]
	v_pk_mul_f32 v[52:53], v[52:53], v[66:67] op_sel_hi:[1,0]
	v_mul_f32_e32 v67, 0xbfb8aa3b, v60
	v_exp_f32_e32 v67, v67
	s_nop 0
	v_add_f32_e32 v67, 1.0, v67
	v_rcp_f32_e32 v68, v67
	v_mul_f32_e32 v67, 0xbfb8aa3b, v61
	v_exp_f32_e32 v67, v67
	s_nop 0
	v_add_f32_e32 v67, 1.0, v67
	v_rcp_f32_e32 v69, v67
	v_pk_mul_f32 v[48:49], v[48:49], v[66:67] op_sel_hi:[1,0]
	v_pk_mul_f32 v[50:51], v[50:51], v[66:67] op_sel_hi:[1,0]
	v_pk_mul_f32 v[60:61], v[60:61], v[68:69]
	s_nop 0
	v_pk_mul_f32 v[52:53], v[52:53], v[60:61]
	s_nop 0
	v_cvt_pk_bf16_f32 v52, v52, v53
	v_mul_f32_e32 v53, 0xbfb8aa3b, v62
	v_exp_f32_e32 v53, v53
	s_nop 0
	v_add_f32_e32 v53, 1.0, v53
	v_rcp_f32_e32 v60, v53
	v_mul_f32_e32 v53, 0xbfb8aa3b, v63
	v_exp_f32_e32 v53, v53
	s_nop 0
	v_add_f32_e32 v53, 1.0, v53
	v_rcp_f32_e32 v61, v53
	s_nop 0
	v_pk_mul_f32 v[60:61], v[62:63], v[60:61]
	s_nop 0
	v_pk_mul_f32 v[54:55], v[54:55], v[60:61]
	s_nop 0
	v_cvt_pk_bf16_f32 v53, v54, v55
	v_pk_mul_f32 v[54:55], v[56:57], v[66:67] op_sel_hi:[1,0]
	global_store_dwordx2 v[64:65], v[52:53], off
	v_mul_f32_e32 v56, 0xbfb8aa3b, v54
	v_mul_f32_e32 v57, 0xbfb8aa3b, v55
	v_exp_f32_e32 v56, v56
	v_exp_f32_e32 v57, v57
	v_pk_mul_f32 v[52:53], v[58:59], v[66:67] op_sel_hi:[1,0]
	v_add_f32_e32 v56, 1.0, v56
	v_add_f32_e32 v57, 1.0, v57
	v_rcp_f32_e32 v56, v56
	v_rcp_f32_e32 v57, v57
	s_nop 0
	v_pk_mul_f32 v[54:55], v[54:55], v[56:57]
	s_nop 0
	v_pk_mul_f32 v[48:49], v[48:49], v[54:55]
	s_nop 0
	v_cvt_pk_bf16_f32 v48, v48, v49
	v_mul_f32_e32 v49, 0xbfb8aa3b, v52
	v_exp_f32_e32 v49, v49
	s_nop 0
	v_add_f32_e32 v49, 1.0, v49
	v_rcp_f32_e32 v54, v49
	v_mul_f32_e32 v49, 0xbfb8aa3b, v53
	v_exp_f32_e32 v49, v49
	s_nop 0
	v_add_f32_e32 v49, 1.0, v49
	v_rcp_f32_e32 v55, v49
	s_nop 0
	v_pk_mul_f32 v[52:53], v[52:53], v[54:55]
	s_nop 0
	v_pk_mul_f32 v[50:51], v[50:51], v[52:53]
	s_nop 0
	v_cvt_pk_bf16_f32 v49, v50, v51
	global_store_dwordx2 v[64:65], v[48:49], off offset:32
	v_add_u32_e32 v48, 0x90, v138
	v_ashrrev_i32_e32 v49, 31, v48
	v_lshl_add_u64 v[50:51], v[48:49], 2, s[14:15]
	v_mov_b32_e32 v50, v155
	v_mad_i64_i32 v[48:49], s[24:25], v48, s4, v[136:137]
	v_lshl_add_u64 v[48:49], v[48:49], 0, s[26:27]
	v_lshl_add_u64 v[48:49], v[48:49], 0, s[54:55]
	v_lshl_add_u64 v[48:49], v[48:49], 0, v[196:197]
	v_pk_mul_f32 v[44:45], v[44:45], v[50:51] op_sel_hi:[1,0]
	v_pk_mul_f32 v[46:47], v[46:47], v[50:51] op_sel_hi:[1,0]
	v_pk_mul_f32 v[38:39], v[38:39], v[50:51] op_sel_hi:[1,0]
	v_pk_mul_f32 v[36:37], v[36:37], v[50:51] op_sel_hi:[1,0]
	v_mul_f32_e32 v51, 0xbfb8aa3b, v44
	v_exp_f32_e32 v51, v51
	s_nop 0
	v_add_f32_e32 v51, 1.0, v51
	v_rcp_f32_e32 v52, v51
	v_mul_f32_e32 v51, 0xbfb8aa3b, v45
	v_exp_f32_e32 v51, v51
	s_nop 0
	v_add_f32_e32 v51, 1.0, v51
	v_rcp_f32_e32 v53, v51
	v_pk_mul_f32 v[32:33], v[32:33], v[50:51] op_sel_hi:[1,0]
	v_pk_mul_f32 v[34:35], v[34:35], v[50:51] op_sel_hi:[1,0]
	v_pk_mul_f32 v[44:45], v[44:45], v[52:53]
	s_nop 0
	v_pk_mul_f32 v[36:37], v[36:37], v[44:45]
	s_nop 0
	v_cvt_pk_bf16_f32 v36, v36, v37
	v_mul_f32_e32 v37, 0xbfb8aa3b, v46
	v_exp_f32_e32 v37, v37
	s_nop 0
	v_add_f32_e32 v37, 1.0, v37
	v_rcp_f32_e32 v44, v37
	v_mul_f32_e32 v37, 0xbfb8aa3b, v47
	v_exp_f32_e32 v37, v37
	s_nop 0
	v_add_f32_e32 v37, 1.0, v37
	v_rcp_f32_e32 v45, v37
	s_nop 0
	v_pk_mul_f32 v[44:45], v[46:47], v[44:45]
	s_nop 0
	v_pk_mul_f32 v[38:39], v[38:39], v[44:45]
	s_nop 0
	v_cvt_pk_bf16_f32 v37, v38, v39
	v_pk_mul_f32 v[38:39], v[40:41], v[50:51] op_sel_hi:[1,0]
	global_store_dwordx2 v[48:49], v[36:37], off
	v_mul_f32_e32 v40, 0xbfb8aa3b, v38
	v_mul_f32_e32 v41, 0xbfb8aa3b, v39
	v_exp_f32_e32 v40, v40
	v_exp_f32_e32 v41, v41
	v_pk_mul_f32 v[36:37], v[42:43], v[50:51] op_sel_hi:[1,0]
	v_add_f32_e32 v40, 1.0, v40
	v_add_f32_e32 v41, 1.0, v41
	v_rcp_f32_e32 v40, v40
	v_rcp_f32_e32 v41, v41
	s_nop 0
	v_pk_mul_f32 v[38:39], v[38:39], v[40:41]
	s_nop 0
	v_pk_mul_f32 v[32:33], v[32:33], v[38:39]
	s_nop 0
	v_cvt_pk_bf16_f32 v32, v32, v33
	v_mul_f32_e32 v33, 0xbfb8aa3b, v36
	v_exp_f32_e32 v33, v33
	s_nop 0
	v_add_f32_e32 v33, 1.0, v33
	v_rcp_f32_e32 v38, v33
	v_mul_f32_e32 v33, 0xbfb8aa3b, v37
	v_exp_f32_e32 v33, v33
	s_nop 0
	v_add_f32_e32 v33, 1.0, v33
	v_rcp_f32_e32 v39, v33
	s_nop 0
	v_pk_mul_f32 v[36:37], v[36:37], v[38:39]
; DEV unsigned cvtpk(float lo, float hi) { f32x2 v = {lo, hi}; bf16x2_t b = __builtin_convertvector(v, bf16x2_t); return __builtin_bit_cast(unsigned, b); }
; DEV float sigm(float x) { return __builtin_amdgcn_rcpf(1.f + __expf(-x)); }
;   __device__ __forceinline__ void operator()(const pg8::f32x4 (&acc)[2][2][4][2], const pg8::Unit& u, int wr, int wc, int fr, int fq) const {
; #pragma unroll
;     for (int ai = 0; ai < 2; ++ai)
; #pragma unroll
;       for (int m = 0; m < 4; ++m) {
;         const int row = u.pm * 256 + ai * 128 + wr * 64 + m * 16 + fr; const float rs = RS[row];
;         bf16_t* rp = TT + (size_t)row * DFF + u.pn * 128 + wc * 32 + 4 * fq;
; #pragma unroll
;         for (int n = 0; n < 2; ++n) {
;           const pg8::f32x4 g = acc[ai][0][m][n] * rs, uu = acc[ai][1][m][n] * rs;
;           u32x2 w; w[0] = cvtpk(g[0] * sigm(g[0]) * uu[0], g[1] * sigm(g[1]) * uu[1]); w[1] = cvtpk(g[2] * sigm(g[2]) * uu[2], g[3] * sigm(g[3]) * uu[3]);
;           *(u32x2*)(rp + n * 16) = w;
;         }
;       }
;   }
	s_nop 0
	v_pk_mul_f32 v[34:35], v[34:35], v[36:37]
	s_nop 0
	v_cvt_pk_bf16_f32 v33, v34, v35
	global_store_dwordx2 v[48:49], v[32:33], off offset:32
	v_add_u32_e32 v32, 0xa0, v138
	v_ashrrev_i32_e32 v33, 31, v32
	v_lshl_add_u64 v[34:35], v[32:33], 2, s[14:15]
	v_mov_b32_e32 v34, v156
	v_mad_i64_i32 v[32:33], s[24:25], v32, s4, v[136:137]
	v_lshl_add_u64 v[32:33], v[32:33], 0, s[26:27]
	v_lshl_add_u64 v[32:33], v[32:33], 0, s[54:55]
	v_lshl_add_u64 v[32:33], v[32:33], 0, v[196:197]
	v_pk_mul_f32 v[28:29], v[28:29], v[34:35] op_sel_hi:[1,0]
	v_pk_mul_f32 v[30:31], v[30:31], v[34:35] op_sel_hi:[1,0]
	v_pk_mul_f32 v[22:23], v[22:23], v[34:35] op_sel_hi:[1,0]
	v_pk_mul_f32 v[20:21], v[20:21], v[34:35] op_sel_hi:[1,0]
	v_mul_f32_e32 v35, 0xbfb8aa3b, v28
	v_exp_f32_e32 v35, v35
	s_nop 0
	v_add_f32_e32 v35, 1.0, v35
	v_rcp_f32_e32 v36, v35
	v_mul_f32_e32 v35, 0xbfb8aa3b, v29
	v_exp_f32_e32 v35, v35
	s_nop 0
	v_add_f32_e32 v35, 1.0, v35
	v_rcp_f32_e32 v37, v35
	v_pk_mul_f32 v[16:17], v[16:17], v[34:35] op_sel_hi:[1,0]
	v_pk_mul_f32 v[18:19], v[18:19], v[34:35] op_sel_hi:[1,0]
	v_pk_mul_f32 v[28:29], v[28:29], v[36:37]
	s_nop 0
	v_pk_mul_f32 v[20:21], v[20:21], v[28:29]
	s_nop 0
	v_cvt_pk_bf16_f32 v20, v20, v21
	v_mul_f32_e32 v21, 0xbfb8aa3b, v30
	v_exp_f32_e32 v21, v21
	s_nop 0
	v_add_f32_e32 v21, 1.0, v21
	v_rcp_f32_e32 v28, v21
	v_mul_f32_e32 v21, 0xbfb8aa3b, v31
	v_exp_f32_e32 v21, v21
	s_nop 0
	v_add_f32_e32 v21, 1.0, v21
	v_rcp_f32_e32 v29, v21
	s_nop 0
	v_pk_mul_f32 v[28:29], v[30:31], v[28:29]
	s_nop 0
	v_pk_mul_f32 v[22:23], v[22:23], v[28:29]
	s_nop 0
	v_cvt_pk_bf16_f32 v21, v22, v23
	v_pk_mul_f32 v[22:23], v[24:25], v[34:35] op_sel_hi:[1,0]
	global_store_dwordx2 v[32:33], v[20:21], off
	v_mul_f32_e32 v24, 0xbfb8aa3b, v22
	v_mul_f32_e32 v25, 0xbfb8aa3b, v23
	v_exp_f32_e32 v24, v24
	v_exp_f32_e32 v25, v25
	v_pk_mul_f32 v[20:21], v[26:27], v[34:35] op_sel_hi:[1,0]
	v_add_f32_e32 v24, 1.0, v24
	v_add_f32_e32 v25, 1.0, v25
	v_rcp_f32_e32 v24, v24
	v_rcp_f32_e32 v25, v25
	s_nop 0
	v_pk_mul_f32 v[22:23], v[22:23], v[24:25]
	s_nop 0
	v_pk_mul_f32 v[16:17], v[16:17], v[22:23]
	s_nop 0
	v_cvt_pk_bf16_f32 v16, v16, v17
	v_mul_f32_e32 v17, 0xbfb8aa3b, v20
	v_exp_f32_e32 v17, v17
	s_nop 0
	v_add_f32_e32 v17, 1.0, v17
	v_rcp_f32_e32 v22, v17
	v_mul_f32_e32 v17, 0xbfb8aa3b, v21
	v_exp_f32_e32 v17, v17
	s_nop 0
	v_add_f32_e32 v17, 1.0, v17
	v_rcp_f32_e32 v23, v17
	s_nop 0
	v_pk_mul_f32 v[20:21], v[20:21], v[22:23]
	s_nop 0
	v_pk_mul_f32 v[18:19], v[18:19], v[20:21]
	s_nop 0
	v_cvt_pk_bf16_f32 v17, v18, v19
	global_store_dwordx2 v[32:33], v[16:17], off offset:32
	v_add_u32_e32 v16, 0xb0, v138
	v_ashrrev_i32_e32 v17, 31, v16
	v_lshl_add_u64 v[18:19], v[16:17], 2, s[14:15]
	v_mov_b32_e32 v18, v157
	v_mad_i64_i32 v[16:17], s[24:25], v16, s4, v[136:137]
	v_lshl_add_u64 v[16:17], v[16:17], 0, s[26:27]
	v_lshl_add_u64 v[16:17], v[16:17], 0, s[54:55]
	v_lshl_add_u64 v[16:17], v[16:17], 0, v[196:197]
	s_mov_b64 s[26:27], -1
	v_pk_mul_f32 v[12:13], v[12:13], v[18:19] op_sel_hi:[1,0]
	v_pk_mul_f32 v[14:15], v[14:15], v[18:19] op_sel_hi:[1,0]
	v_pk_mul_f32 v[6:7], v[6:7], v[18:19] op_sel_hi:[1,0]
	v_pk_mul_f32 v[4:5], v[4:5], v[18:19] op_sel_hi:[1,0]
	v_mul_f32_e32 v19, 0xbfb8aa3b, v12
	v_exp_f32_e32 v19, v19
	s_nop 0
	v_add_f32_e32 v19, 1.0, v19
	v_rcp_f32_e32 v20, v19
	v_mul_f32_e32 v19, 0xbfb8aa3b, v13
	v_exp_f32_e32 v19, v19
	s_nop 0
	v_add_f32_e32 v19, 1.0, v19
	v_rcp_f32_e32 v21, v19
	v_pk_mul_f32 v[0:1], v[0:1], v[18:19] op_sel_hi:[1,0]
	v_pk_mul_f32 v[2:3], v[2:3], v[18:19] op_sel_hi:[1,0]
	v_pk_mul_f32 v[12:13], v[12:13], v[20:21]
	s_nop 0
	v_pk_mul_f32 v[4:5], v[4:5], v[12:13]
	s_nop 0
	v_cvt_pk_bf16_f32 v4, v4, v5
	v_mul_f32_e32 v5, 0xbfb8aa3b, v14
	v_exp_f32_e32 v5, v5
	s_nop 0
	v_add_f32_e32 v5, 1.0, v5
	v_rcp_f32_e32 v12, v5
	v_mul_f32_e32 v5, 0xbfb8aa3b, v15
	v_exp_f32_e32 v5, v5
	s_nop 0
	v_add_f32_e32 v5, 1.0, v5
	v_rcp_f32_e32 v13, v5
	s_nop 0
	v_pk_mul_f32 v[12:13], v[14:15], v[12:13]
	s_nop 0
	v_pk_mul_f32 v[6:7], v[6:7], v[12:13]
	s_nop 0
	v_cvt_pk_bf16_f32 v5, v6, v7
	v_pk_mul_f32 v[6:7], v[8:9], v[18:19] op_sel_hi:[1,0]
	global_store_dwordx2 v[16:17], v[4:5], off
	v_mul_f32_e32 v8, 0xbfb8aa3b, v6
	v_mul_f32_e32 v9, 0xbfb8aa3b, v7
	v_exp_f32_e32 v8, v8
	v_exp_f32_e32 v9, v9
	v_pk_mul_f32 v[4:5], v[10:11], v[18:19] op_sel_hi:[1,0]
	v_add_f32_e32 v8, 1.0, v8
	v_add_f32_e32 v9, 1.0, v9
	v_rcp_f32_e32 v8, v8
	v_rcp_f32_e32 v9, v9
	s_nop 0
	v_pk_mul_f32 v[6:7], v[6:7], v[8:9]
	s_nop 0
	v_pk_mul_f32 v[0:1], v[0:1], v[6:7]
	s_nop 0
	v_cvt_pk_bf16_f32 v0, v0, v1
	v_mul_f32_e32 v1, 0xbfb8aa3b, v4
	v_exp_f32_e32 v1, v1
	s_nop 0
	v_add_f32_e32 v1, 1.0, v1
	v_rcp_f32_e32 v6, v1
	v_mul_f32_e32 v1, 0xbfb8aa3b, v5
	v_exp_f32_e32 v1, v1
	s_nop 0
	v_add_f32_e32 v1, 1.0, v1
	v_rcp_f32_e32 v7, v1
	s_nop 0
	v_pk_mul_f32 v[4:5], v[4:5], v[6:7]
	s_nop 0
	v_pk_mul_f32 v[2:3], v[2:3], v[4:5]
	s_nop 0
	v_cvt_pk_bf16_f32 v1, v2, v3
	global_store_dwordx2 v[16:17], v[0:1], off offset:32
	s_cbranch_vccnz .LBB0_386
	s_andn2_b64 vcc, exec, s[0:1]
	s_cbranch_vccnz .LBB0_385
	s_barrier
	s_branch .LBB0_385

; DEV unsigned cvtpk(float lo, float hi) { f32x2 v = {lo, hi}; bf16x2_t b = __builtin_convertvector(v, bf16x2_t); return __builtin_bit_cast(unsigned, b); }
; DEV float gelu_t(float x) { float z = 0.7978845608f * (x + 0.044715f * x * x * x); return x * __builtin_amdgcn_rcpf(1.f + __expf(-2.f * z)); }
; DEV float sigm(float x) { return __builtin_amdgcn_rcpf(1.f + __expf(-x)); }
;   __device__ __forceinline__ void operator()(const pg8::f32x4 (&acc)[2][2][4][2], const pg8::Unit& u, int wr, int wc, int fr, int fq) const {
; #pragma unroll
;     for (int bj = 0; bj < 2; ++bj) {
;       const int cb = u.pn * 256 + bj * 128 + wc * 32;
;       if (cb >= C_END) continue;
;       const int kind = cb < C_CQL ? 0 : ((cb < C_KR || (cb >= C_VV && cb < C_G)) ? 1 : (cb < C_Q ? 2 : (cb < C_VV ? 3 : 4)));
;       const int c0 = cb + 8 * fq;
; #pragma unroll
;       for (int ai = 0; ai < 2; ++ai)
; #pragma unroll
;         for (int m = 0; m < 4; ++m) {
;           const int row = u.pm * 256 + ai * 128 + wr * 64 + m * 16 + fr; const float rs = RS[row]; const int pos = row & seqmask;
;           u32x4 w;
; #pragma unroll
;           for (int n = 0; n < 2; ++n) {
;             pg8::f32x4 v = acc[ai][bj][m][n] * rs;
;             if (kind == 0) { v[0] = gelu_t(v[0]); v[1] = gelu_t(v[1]); v[2] = gelu_t(v[2]); v[3] = gelu_t(v[3]); }
;             else if (kind == 4) { v[0] = sigm(v[0]); v[1] = sigm(v[1]); v[2] = sigm(v[2]); v[3] = sigm(v[3]); }
;             else if (kind == 3 || kind == 2) {
;               const pg8::f32x4 cs = kind == 3 ? *(const pg8::f32x4*)(R128 + pos * 64 + ((((c0 + 4 * n) - C_Q) & 127) >> 1))
;                                               : *(const pg8::f32x4*)(R64 + pos * 32 + (((c0 + 4 * n) - C_KR) >> 1));
;               const float a0 = v[0] * cs[0] - v[1] * cs[1], a1 = v[1] * cs[0] + v[0] * cs[1], a2 = v[2] * cs[2] - v[3] * cs[3], a3 = v[3] * cs[2] + v[2] * cs[3];
;               v[0] = a0; v[1] = a1; v[2] = a2; v[3] = a3;
;             }
;             w[2 * n] = cvtpk(v[0], v[1]); w[2 * n + 1] = cvtpk(v[2], v[3]);
;           }
.LBB0_1290:
	s_lshl_b32 s4, s34, 8
	v_add_u32_e32 v184, s4, v158
	v_ashrrev_i32_e32 v185, 31, v184
	v_lshl_add_u64 v[186:187], v[184:185], 2, s[12:13]
	global_load_dword v176, v[186:187], off
	v_add_u32_e32 v184, s4, v161
	v_ashrrev_i32_e32 v185, 31, v184
	v_lshl_add_u64 v[186:187], v[184:185], 2, s[12:13]
	global_load_dword v177, v[186:187], off
	v_add_u32_e32 v184, s4, v162
	v_ashrrev_i32_e32 v185, 31, v184
	v_lshl_add_u64 v[186:187], v[184:185], 2, s[12:13]
	global_load_dword v178, v[186:187], off
	v_add_u32_e32 v184, s4, v163
	v_ashrrev_i32_e32 v185, 31, v184
	v_lshl_add_u64 v[186:187], v[184:185], 2, s[12:13]
	global_load_dword v179, v[186:187], off
	v_add_u32_e32 v184, s4, v164
	v_ashrrev_i32_e32 v185, 31, v184
	v_lshl_add_u64 v[186:187], v[184:185], 2, s[12:13]
	global_load_dword v180, v[186:187], off
	v_add_u32_e32 v184, s4, v165
	v_ashrrev_i32_e32 v185, 31, v184
	v_lshl_add_u64 v[186:187], v[184:185], 2, s[12:13]
	global_load_dword v181, v[186:187], off
	v_add_u32_e32 v184, s4, v166
	v_ashrrev_i32_e32 v185, 31, v184
	v_lshl_add_u64 v[186:187], v[184:185], 2, s[12:13]
	global_load_dword v182, v[186:187], off
	v_add_u32_e32 v184, s4, v167
	v_ashrrev_i32_e32 v185, 31, v184
	v_lshl_add_u64 v[186:187], v[184:185], 2, s[12:13]
	global_load_dword v183, v[186:187], off
	s_waitcnt vmcnt(0)
	s_lshl_b32 s86, s18, 8
	s_or_b32 s35, s86, s68
	s_cmpk_gt_i32 s35, 0x1cbf
	s_cbranch_scc1 .LBB0_1517
	s_cmpk_lt_i32 s35, 0x800
	s_mov_b32 s1, 0
	s_cbranch_scc1 .LBB0_1293
	v_sub_co_u32_e32 v142, vcc, s35, v210
	s_cmpk_lt_u32 s86, 0xa80
	v_readfirstlane_b32 s1, v142
	s_cselect_b64 s[18:19], -1, 0
	s_cmpk_lt_u32 s1, 0x100
	s_cselect_b64 s[26:27], -1, 0
	s_or_b64 s[18:19], s[18:19], s[26:27]
	s_and_b64 s[26:27], vcc, exec
	s_cselect_b32 s1, 3, 4
	s_cmpk_gt_u32 s35, 0xabf
	s_cselect_b32 s1, s1, 2
	s_and_b64 s[18:19], s[18:19], exec
	s_cselect_b32 s1, 1, s1
.LBB0_1293:
	s_and_b32 s18, s1, 6
	s_cmp_eq_u32 s18, 2
	s_cselect_b64 s[26:27], -1, 0
	s_cmp_lg_u32 s1, 3
	s_cselect_b64 s[18:19], -1, 0
	s_lshl_b32 s25, s34, 8
	v_add_u32_e32 v142, s25, v158
	v_ashrrev_i32_e32 v143, 31, v142
	v_lshl_add_u64 v[144:145], v[142:143], 2, s[12:13]
	v_mov_b32_e32 v152, v176
	s_cmp_gt_i32 s1, 3
	s_mov_b64 s[40:41], -1
	v_pk_mul_f32 v[156:157], v[126:127], v[152:153] op_sel_hi:[1,0]
	v_pk_mul_f32 v[154:155], v[124:125], v[152:153] op_sel_hi:[1,0]
	s_cbranch_scc0 .LBB0_1295
	v_mul_f32_e32 v124, 0xbfb8aa3b, v154
	v_exp_f32_e32 v124, v124
	v_mul_f32_e32 v125, 0xbfb8aa3b, v155
	v_mul_f32_e32 v127, 0xbfb8aa3b, v157
	v_exp_f32_e32 v125, v125
	v_add_f32_e32 v124, 1.0, v124
	v_rcp_f32_e32 v126, v124
	v_mul_f32_e32 v124, 0xbfb8aa3b, v156
	v_exp_f32_e32 v124, v124
	v_exp_f32_e32 v143, v127
	v_add_f32_e32 v125, 1.0, v125
	v_rcp_f32_e32 v127, v125
	v_add_f32_e32 v124, 1.0, v124
	v_rcp_f32_e32 v144, v124
	v_add_f32_e32 v124, 1.0, v143
	v_rcp_f32_e32 v146, v124
	s_mov_b64 s[40:41], 0

; DEV unsigned cvtpk(float lo, float hi) { f32x2 v = {lo, hi}; bf16x2_t b = __builtin_convertvector(v, bf16x2_t); return __builtin_bit_cast(unsigned, b); }
; DEV float gelu_t(float x) { float z = 0.7978845608f * (x + 0.044715f * x * x * x); return x * __builtin_amdgcn_rcpf(1.f + __expf(-2.f * z)); }
; DEV float sigm(float x) { return __builtin_amdgcn_rcpf(1.f + __expf(-x)); }
;   __device__ __forceinline__ void operator()(const pg8::f32x4 (&acc)[2][2][4][2], const pg8::Unit& u, int wr, int wc, int fr, int fq) const {
;     ...
;           const int row = u.pm * 256 + ai * 128 + wr * 64 + m * 16 + fr; const float rs = RS[row]; const int pos = row & seqmask;
;           u32x4 w;
; #pragma unroll
;           for (int n = 0; n < 2; ++n) {
;             pg8::f32x4 v = acc[ai][bj][m][n] * rs;
;             if (kind == 0) { v[0] = gelu_t(v[0]); v[1] = gelu_t(v[1]); v[2] = gelu_t(v[2]); v[3] = gelu_t(v[3]); }
;             else if (kind == 4) { v[0] = sigm(v[0]); v[1] = sigm(v[1]); v[2] = sigm(v[2]); v[3] = sigm(v[3]); }
;             else if (kind == 3 || kind == 2) {
;               const pg8::f32x4 cs = kind == 3 ? *(const pg8::f32x4*)(R128 + pos * 64 + ((((c0 + 4 * n) - C_Q) & 127) >> 1))
;                                               : *(const pg8::f32x4*)(R64 + pos * 32 + (((c0 + 4 * n) - C_KR) >> 1));
;               const float a0 = v[0] * cs[0] - v[1] * cs[1], a1 = v[1] * cs[0] + v[0] * cs[1], a2 = v[2] * cs[2] - v[3] * cs[3], a3 = v[3] * cs[2] + v[2] * cs[3];
;               v[0] = a0; v[1] = a1; v[2] = a2; v[3] = a3;
;             }
;             w[2 * n] = cvtpk(v[0], v[1]); w[2 * n + 1] = cvtpk(v[2], v[3]);
;           }
.LBB0_1321:
	s_nop 1
	v_add_u32_e32 v120, s25, v161
	v_ashrrev_i32_e32 v121, 31, v120
	v_lshl_add_u64 v[122:123], v[120:121], 2, s[12:13]
	v_mov_b32_e32 v144, v177
	s_cmp_gt_i32 s1, 3
	s_mov_b64 s[40:41], -1
	v_pk_mul_f32 v[148:149], v[118:119], v[144:145] op_sel_hi:[1,0]
	v_pk_mul_f32 v[146:147], v[116:117], v[144:145] op_sel_hi:[1,0]
	s_cbranch_scc0 .LBB0_1323
	v_mul_f32_e32 v116, 0xbfb8aa3b, v146
	v_mul_f32_e32 v117, 0xbfb8aa3b, v147
	v_mul_f32_e32 v118, 0xbfb8aa3b, v148
	v_mul_f32_e32 v119, 0xbfb8aa3b, v149
	v_exp_f32_e32 v116, v116
	v_exp_f32_e32 v117, v117
	v_exp_f32_e32 v118, v118
	v_exp_f32_e32 v119, v119
	v_add_f32_e32 v116, 1.0, v116
	v_add_f32_e32 v117, 1.0, v117
	v_add_f32_e32 v118, 1.0, v118
	v_add_f32_e32 v119, 1.0, v119
	v_rcp_f32_e32 v116, v116
	v_rcp_f32_e32 v117, v117
	v_rcp_f32_e32 v118, v118
	v_rcp_f32_e32 v122, v119
	s_mov_b64 s[40:41], 0

; DEV unsigned cvtpk(float lo, float hi) { f32x2 v = {lo, hi}; bf16x2_t b = __builtin_convertvector(v, bf16x2_t); return __builtin_bit_cast(unsigned, b); }
; DEV float gelu_t(float x) { float z = 0.7978845608f * (x + 0.044715f * x * x * x); return x * __builtin_amdgcn_rcpf(1.f + __expf(-2.f * z)); }
; DEV float sigm(float x) { return __builtin_amdgcn_rcpf(1.f + __expf(-x)); }
;   __device__ __forceinline__ void operator()(const pg8::f32x4 (&acc)[2][2][4][2], const pg8::Unit& u, int wr, int wc, int fr, int fq) const {
;     ...
;           const int row = u.pm * 256 + ai * 128 + wr * 64 + m * 16 + fr; const float rs = RS[row]; const int pos = row & seqmask;
;           u32x4 w;
; #pragma unroll
;           for (int n = 0; n < 2; ++n) {
;             pg8::f32x4 v = acc[ai][bj][m][n] * rs;
;             if (kind == 0) { v[0] = gelu_t(v[0]); v[1] = gelu_t(v[1]); v[2] = gelu_t(v[2]); v[3] = gelu_t(v[3]); }
;             else if (kind == 4) { v[0] = sigm(v[0]); v[1] = sigm(v[1]); v[2] = sigm(v[2]); v[3] = sigm(v[3]); }
;             else if (kind == 3 || kind == 2) {
;               const pg8::f32x4 cs = kind == 3 ? *(const pg8::f32x4*)(R128 + pos * 64 + ((((c0 + 4 * n) - C_Q) & 127) >> 1))
;                                               : *(const pg8::f32x4*)(R64 + pos * 32 + (((c0 + 4 * n) - C_KR) >> 1));
;               const float a0 = v[0] * cs[0] - v[1] * cs[1], a1 = v[1] * cs[0] + v[0] * cs[1], a2 = v[2] * cs[2] - v[3] * cs[3], a3 = v[3] * cs[2] + v[2] * cs[3];
;               v[0] = a0; v[1] = a1; v[2] = a2; v[3] = a3;
;             }
;             w[2 * n] = cvtpk(v[0], v[1]); w[2 * n + 1] = cvtpk(v[2], v[3]);
;           }
.LBB0_1349:
	s_nop 1
	v_add_u32_e32 v112, s25, v162
	v_ashrrev_i32_e32 v113, 31, v112
	v_lshl_add_u64 v[114:115], v[112:113], 2, s[12:13]
	v_mov_b32_e32 v120, v178
	s_cmp_gt_i32 s1, 3
	s_mov_b64 s[90:91], -1
	v_pk_mul_f32 v[126:127], v[110:111], v[120:121] op_sel_hi:[1,0]
	v_pk_mul_f32 v[122:123], v[108:109], v[120:121] op_sel_hi:[1,0]
	s_cbranch_scc0 .LBB0_1351
	v_mul_f32_e32 v108, 0xbfb8aa3b, v122
	v_mul_f32_e32 v109, 0xbfb8aa3b, v123
	v_mul_f32_e32 v110, 0xbfb8aa3b, v126
	v_mul_f32_e32 v111, 0xbfb8aa3b, v127
	v_exp_f32_e32 v108, v108
	v_exp_f32_e32 v109, v109
	v_exp_f32_e32 v110, v110
	v_exp_f32_e32 v111, v111
	v_add_f32_e32 v108, 1.0, v108
	v_add_f32_e32 v109, 1.0, v109
	v_add_f32_e32 v110, 1.0, v110
	v_add_f32_e32 v111, 1.0, v111
	v_rcp_f32_e32 v108, v108
	v_rcp_f32_e32 v109, v109
	v_rcp_f32_e32 v110, v110
	v_rcp_f32_e32 v114, v111
	s_mov_b64 s[90:91], 0

; DEV unsigned cvtpk(float lo, float hi) { f32x2 v = {lo, hi}; bf16x2_t b = __builtin_convertvector(v, bf16x2_t); return __builtin_bit_cast(unsigned, b); }
; DEV float gelu_t(float x) { float z = 0.7978845608f * (x + 0.044715f * x * x * x); return x * __builtin_amdgcn_rcpf(1.f + __expf(-2.f * z)); }
; DEV float sigm(float x) { return __builtin_amdgcn_rcpf(1.f + __expf(-x)); }
;   __device__ __forceinline__ void operator()(const pg8::f32x4 (&acc)[2][2][4][2], const pg8::Unit& u, int wr, int wc, int fr, int fq) const {
;     ...
;           const int row = u.pm * 256 + ai * 128 + wr * 64 + m * 16 + fr; const float rs = RS[row]; const int pos = row & seqmask;
;           u32x4 w;
; #pragma unroll
;           for (int n = 0; n < 2; ++n) {
;             pg8::f32x4 v = acc[ai][bj][m][n] * rs;
;             if (kind == 0) { v[0] = gelu_t(v[0]); v[1] = gelu_t(v[1]); v[2] = gelu_t(v[2]); v[3] = gelu_t(v[3]); }
;             else if (kind == 4) { v[0] = sigm(v[0]); v[1] = sigm(v[1]); v[2] = sigm(v[2]); v[3] = sigm(v[3]); }
;             else if (kind == 3 || kind == 2) {
;               const pg8::f32x4 cs = kind == 3 ? *(const pg8::f32x4*)(R128 + pos * 64 + ((((c0 + 4 * n) - C_Q) & 127) >> 1))
;                                               : *(const pg8::f32x4*)(R64 + pos * 32 + (((c0 + 4 * n) - C_KR) >> 1));
;               const float a0 = v[0] * cs[0] - v[1] * cs[1], a1 = v[1] * cs[0] + v[0] * cs[1], a2 = v[2] * cs[2] - v[3] * cs[3], a3 = v[3] * cs[2] + v[2] * cs[3];
;               v[0] = a0; v[1] = a1; v[2] = a2; v[3] = a3;
;             }
;             w[2 * n] = cvtpk(v[0], v[1]); w[2 * n + 1] = cvtpk(v[2], v[3]);
;           }
.LBB0_1377:
	s_nop 1
	v_add_u32_e32 v104, s25, v163
	v_ashrrev_i32_e32 v105, 31, v104
	v_lshl_add_u64 v[106:107], v[104:105], 2, s[12:13]
	v_mov_b32_e32 v112, v179
	s_cmp_gt_i32 s1, 3
	s_mov_b64 s[90:91], -1
	v_pk_mul_f32 v[116:117], v[102:103], v[112:113] op_sel_hi:[1,0]
	v_pk_mul_f32 v[114:115], v[100:101], v[112:113] op_sel_hi:[1,0]
	s_cbranch_scc0 .LBB0_1379
	v_mul_f32_e32 v100, 0xbfb8aa3b, v114
	v_mul_f32_e32 v101, 0xbfb8aa3b, v115
	v_mul_f32_e32 v102, 0xbfb8aa3b, v116
	v_mul_f32_e32 v103, 0xbfb8aa3b, v117
	v_exp_f32_e32 v100, v100
	v_exp_f32_e32 v101, v101
	v_exp_f32_e32 v102, v102
	v_exp_f32_e32 v103, v103
	v_add_f32_e32 v100, 1.0, v100
	v_add_f32_e32 v101, 1.0, v101
	v_add_f32_e32 v102, 1.0, v102
	v_add_f32_e32 v103, 1.0, v103
	v_rcp_f32_e32 v100, v100
	v_rcp_f32_e32 v101, v101
	v_rcp_f32_e32 v102, v102
	v_rcp_f32_e32 v106, v103
	s_mov_b64 s[90:91], 0

; DEV unsigned cvtpk(float lo, float hi) { f32x2 v = {lo, hi}; bf16x2_t b = __builtin_convertvector(v, bf16x2_t); return __builtin_bit_cast(unsigned, b); }
; DEV float gelu_t(float x) { float z = 0.7978845608f * (x + 0.044715f * x * x * x); return x * __builtin_amdgcn_rcpf(1.f + __expf(-2.f * z)); }
; DEV float sigm(float x) { return __builtin_amdgcn_rcpf(1.f + __expf(-x)); }
;   __device__ __forceinline__ void operator()(const pg8::f32x4 (&acc)[2][2][4][2], const pg8::Unit& u, int wr, int wc, int fr, int fq) const {
;     ...
;           const int row = u.pm * 256 + ai * 128 + wr * 64 + m * 16 + fr; const float rs = RS[row]; const int pos = row & seqmask;
;           u32x4 w;
; #pragma unroll
;           for (int n = 0; n < 2; ++n) {
;             pg8::f32x4 v = acc[ai][bj][m][n] * rs;
;             if (kind == 0) { v[0] = gelu_t(v[0]); v[1] = gelu_t(v[1]); v[2] = gelu_t(v[2]); v[3] = gelu_t(v[3]); }
;             else if (kind == 4) { v[0] = sigm(v[0]); v[1] = sigm(v[1]); v[2] = sigm(v[2]); v[3] = sigm(v[3]); }
;             else if (kind == 3 || kind == 2) {
;               const pg8::f32x4 cs = kind == 3 ? *(const pg8::f32x4*)(R128 + pos * 64 + ((((c0 + 4 * n) - C_Q) & 127) >> 1))
;                                               : *(const pg8::f32x4*)(R64 + pos * 32 + (((c0 + 4 * n) - C_KR) >> 1));
;               const float a0 = v[0] * cs[0] - v[1] * cs[1], a1 = v[1] * cs[0] + v[0] * cs[1], a2 = v[2] * cs[2] - v[3] * cs[3], a3 = v[3] * cs[2] + v[2] * cs[3];
;               v[0] = a0; v[1] = a1; v[2] = a2; v[3] = a3;
;             }
;             w[2 * n] = cvtpk(v[0], v[1]); w[2 * n + 1] = cvtpk(v[2], v[3]);
;           }
.LBB0_1405:
	s_nop 1
	v_add_u32_e32 v96, s25, v164
	v_ashrrev_i32_e32 v97, 31, v96
	v_lshl_add_u64 v[98:99], v[96:97], 2, s[12:13]
	v_mov_b32_e32 v104, v180
	s_cmp_gt_i32 s1, 3
	s_mov_b64 s[90:91], -1
	v_pk_mul_f32 v[108:109], v[94:95], v[104:105] op_sel_hi:[1,0]
	v_pk_mul_f32 v[106:107], v[92:93], v[104:105] op_sel_hi:[1,0]
	s_cbranch_scc0 .LBB0_1407
	v_mul_f32_e32 v92, 0xbfb8aa3b, v106
	v_mul_f32_e32 v93, 0xbfb8aa3b, v107
	v_mul_f32_e32 v94, 0xbfb8aa3b, v108
	v_mul_f32_e32 v95, 0xbfb8aa3b, v109
	v_exp_f32_e32 v92, v92
	v_exp_f32_e32 v93, v93
	v_exp_f32_e32 v94, v94
	v_exp_f32_e32 v95, v95
	v_add_f32_e32 v92, 1.0, v92
	v_add_f32_e32 v93, 1.0, v93
	v_add_f32_e32 v94, 1.0, v94
	v_add_f32_e32 v95, 1.0, v95
	v_rcp_f32_e32 v92, v92
	v_rcp_f32_e32 v93, v93
	v_rcp_f32_e32 v94, v94
	v_rcp_f32_e32 v98, v95
	s_mov_b64 s[90:91], 0

; DEV unsigned cvtpk(float lo, float hi) { f32x2 v = {lo, hi}; bf16x2_t b = __builtin_convertvector(v, bf16x2_t); return __builtin_bit_cast(unsigned, b); }
; DEV float gelu_t(float x) { float z = 0.7978845608f * (x + 0.044715f * x * x * x); return x * __builtin_amdgcn_rcpf(1.f + __expf(-2.f * z)); }
; DEV float sigm(float x) { return __builtin_amdgcn_rcpf(1.f + __expf(-x)); }
;   __device__ __forceinline__ void operator()(const pg8::f32x4 (&acc)[2][2][4][2], const pg8::Unit& u, int wr, int wc, int fr, int fq) const {
;     ...
;           const int row = u.pm * 256 + ai * 128 + wr * 64 + m * 16 + fr; const float rs = RS[row]; const int pos = row & seqmask;
;           u32x4 w;
; #pragma unroll
;           for (int n = 0; n < 2; ++n) {
;             pg8::f32x4 v = acc[ai][bj][m][n] * rs;
;             if (kind == 0) { v[0] = gelu_t(v[0]); v[1] = gelu_t(v[1]); v[2] = gelu_t(v[2]); v[3] = gelu_t(v[3]); }
;             else if (kind == 4) { v[0] = sigm(v[0]); v[1] = sigm(v[1]); v[2] = sigm(v[2]); v[3] = sigm(v[3]); }
;             else if (kind == 3 || kind == 2) {
;               const pg8::f32x4 cs = kind == 3 ? *(const pg8::f32x4*)(R128 + pos * 64 + ((((c0 + 4 * n) - C_Q) & 127) >> 1))
;                                               : *(const pg8::f32x4*)(R64 + pos * 32 + (((c0 + 4 * n) - C_KR) >> 1));
;               const float a0 = v[0] * cs[0] - v[1] * cs[1], a1 = v[1] * cs[0] + v[0] * cs[1], a2 = v[2] * cs[2] - v[3] * cs[3], a3 = v[3] * cs[2] + v[2] * cs[3];
;               v[0] = a0; v[1] = a1; v[2] = a2; v[3] = a3;
;             }
;             w[2 * n] = cvtpk(v[0], v[1]); w[2 * n + 1] = cvtpk(v[2], v[3]);
;           }
.LBB0_1433:
	s_nop 1
	v_add_u32_e32 v88, s25, v165
	v_ashrrev_i32_e32 v89, 31, v88
	v_lshl_add_u64 v[90:91], v[88:89], 2, s[12:13]
	v_mov_b32_e32 v96, v181
	s_cmp_gt_i32 s1, 3
	s_mov_b64 s[90:91], -1
	v_pk_mul_f32 v[100:101], v[86:87], v[96:97] op_sel_hi:[1,0]
	v_pk_mul_f32 v[98:99], v[84:85], v[96:97] op_sel_hi:[1,0]
	s_cbranch_scc0 .LBB0_1435
	v_mul_f32_e32 v84, 0xbfb8aa3b, v98
	v_mul_f32_e32 v85, 0xbfb8aa3b, v99
	v_mul_f32_e32 v86, 0xbfb8aa3b, v100
	v_mul_f32_e32 v87, 0xbfb8aa3b, v101
	v_exp_f32_e32 v84, v84
	v_exp_f32_e32 v85, v85
	v_exp_f32_e32 v86, v86
	v_exp_f32_e32 v87, v87
	v_add_f32_e32 v84, 1.0, v84
	v_add_f32_e32 v85, 1.0, v85
	v_add_f32_e32 v86, 1.0, v86
	v_add_f32_e32 v87, 1.0, v87
	v_rcp_f32_e32 v84, v84
	v_rcp_f32_e32 v85, v85
	v_rcp_f32_e32 v86, v86
	v_rcp_f32_e32 v90, v87
	s_mov_b64 s[90:91], 0

; DEV unsigned cvtpk(float lo, float hi) { f32x2 v = {lo, hi}; bf16x2_t b = __builtin_convertvector(v, bf16x2_t); return __builtin_bit_cast(unsigned, b); }
; DEV float gelu_t(float x) { float z = 0.7978845608f * (x + 0.044715f * x * x * x); return x * __builtin_amdgcn_rcpf(1.f + __expf(-2.f * z)); }
; DEV float sigm(float x) { return __builtin_amdgcn_rcpf(1.f + __expf(-x)); }
;   __device__ __forceinline__ void operator()(const pg8::f32x4 (&acc)[2][2][4][2], const pg8::Unit& u, int wr, int wc, int fr, int fq) const {
;     ...
;           const int row = u.pm * 256 + ai * 128 + wr * 64 + m * 16 + fr; const float rs = RS[row]; const int pos = row & seqmask;
;           u32x4 w;
; #pragma unroll
;           for (int n = 0; n < 2; ++n) {
;             pg8::f32x4 v = acc[ai][bj][m][n] * rs;
;             if (kind == 0) { v[0] = gelu_t(v[0]); v[1] = gelu_t(v[1]); v[2] = gelu_t(v[2]); v[3] = gelu_t(v[3]); }
;             else if (kind == 4) { v[0] = sigm(v[0]); v[1] = sigm(v[1]); v[2] = sigm(v[2]); v[3] = sigm(v[3]); }
;             else if (kind == 3 || kind == 2) {
;               const pg8::f32x4 cs = kind == 3 ? *(const pg8::f32x4*)(R128 + pos * 64 + ((((c0 + 4 * n) - C_Q) & 127) >> 1))
;                                               : *(const pg8::f32x4*)(R64 + pos * 32 + (((c0 + 4 * n) - C_KR) >> 1));
;               const float a0 = v[0] * cs[0] - v[1] * cs[1], a1 = v[1] * cs[0] + v[0] * cs[1], a2 = v[2] * cs[2] - v[3] * cs[3], a3 = v[3] * cs[2] + v[2] * cs[3];
;               v[0] = a0; v[1] = a1; v[2] = a2; v[3] = a3;
;             }
;             w[2 * n] = cvtpk(v[0], v[1]); w[2 * n + 1] = cvtpk(v[2], v[3]);
;           }
.LBB0_1461:
	s_nop 1
	v_add_u32_e32 v80, s25, v166
	v_ashrrev_i32_e32 v81, 31, v80
	v_lshl_add_u64 v[82:83], v[80:81], 2, s[12:13]
	v_mov_b32_e32 v88, v182
	s_cmp_gt_i32 s1, 3
	s_mov_b64 s[90:91], -1
	v_pk_mul_f32 v[92:93], v[78:79], v[88:89] op_sel_hi:[1,0]
	v_pk_mul_f32 v[90:91], v[76:77], v[88:89] op_sel_hi:[1,0]
	s_cbranch_scc0 .LBB0_1463
	v_mul_f32_e32 v76, 0xbfb8aa3b, v90
	v_mul_f32_e32 v77, 0xbfb8aa3b, v91
	v_mul_f32_e32 v78, 0xbfb8aa3b, v92
	v_mul_f32_e32 v79, 0xbfb8aa3b, v93
	v_exp_f32_e32 v76, v76
	v_exp_f32_e32 v77, v77
	v_exp_f32_e32 v78, v78
	v_exp_f32_e32 v79, v79
	v_add_f32_e32 v76, 1.0, v76
	v_add_f32_e32 v77, 1.0, v77
	v_add_f32_e32 v78, 1.0, v78
	v_add_f32_e32 v79, 1.0, v79
	v_rcp_f32_e32 v76, v76
	v_rcp_f32_e32 v77, v77
	v_rcp_f32_e32 v78, v78
	v_rcp_f32_e32 v82, v79
	s_mov_b64 s[90:91], 0

; DEV unsigned cvtpk(float lo, float hi) { f32x2 v = {lo, hi}; bf16x2_t b = __builtin_convertvector(v, bf16x2_t); return __builtin_bit_cast(unsigned, b); }
; DEV float gelu_t(float x) { float z = 0.7978845608f * (x + 0.044715f * x * x * x); return x * __builtin_amdgcn_rcpf(1.f + __expf(-2.f * z)); }
; DEV float sigm(float x) { return __builtin_amdgcn_rcpf(1.f + __expf(-x)); }
;   __device__ __forceinline__ void operator()(const pg8::f32x4 (&acc)[2][2][4][2], const pg8::Unit& u, int wr, int wc, int fr, int fq) const {
;     ...
;           const int row = u.pm * 256 + ai * 128 + wr * 64 + m * 16 + fr; const float rs = RS[row]; const int pos = row & seqmask;
;           u32x4 w;
; #pragma unroll
;           for (int n = 0; n < 2; ++n) {
;             pg8::f32x4 v = acc[ai][bj][m][n] * rs;
;             if (kind == 0) { v[0] = gelu_t(v[0]); v[1] = gelu_t(v[1]); v[2] = gelu_t(v[2]); v[3] = gelu_t(v[3]); }
;             else if (kind == 4) { v[0] = sigm(v[0]); v[1] = sigm(v[1]); v[2] = sigm(v[2]); v[3] = sigm(v[3]); }
;             else if (kind == 3 || kind == 2) {
;               const pg8::f32x4 cs = kind == 3 ? *(const pg8::f32x4*)(R128 + pos * 64 + ((((c0 + 4 * n) - C_Q) & 127) >> 1))
;                                               : *(const pg8::f32x4*)(R64 + pos * 32 + (((c0 + 4 * n) - C_KR) >> 1));
;               const float a0 = v[0] * cs[0] - v[1] * cs[1], a1 = v[1] * cs[0] + v[0] * cs[1], a2 = v[2] * cs[2] - v[3] * cs[3], a3 = v[3] * cs[2] + v[2] * cs[3];
;               v[0] = a0; v[1] = a1; v[2] = a2; v[3] = a3;
;             }
;             w[2 * n] = cvtpk(v[0], v[1]); w[2 * n + 1] = cvtpk(v[2], v[3]);
;           }
.LBB0_1489:
	s_nop 1
	v_add_u32_e32 v72, s25, v167
	v_ashrrev_i32_e32 v73, 31, v72
	v_lshl_add_u64 v[74:75], v[72:73], 2, s[12:13]
	v_mov_b32_e32 v80, v183
	s_cmp_gt_i32 s1, 3
	s_mov_b64 s[90:91], -1
	v_pk_mul_f32 v[84:85], v[70:71], v[80:81] op_sel_hi:[1,0]
	v_pk_mul_f32 v[82:83], v[68:69], v[80:81] op_sel_hi:[1,0]
	s_cbranch_scc0 .LBB0_1491
	v_mul_f32_e32 v68, 0xbfb8aa3b, v82
	v_mul_f32_e32 v69, 0xbfb8aa3b, v83
	v_mul_f32_e32 v70, 0xbfb8aa3b, v84
	v_mul_f32_e32 v71, 0xbfb8aa3b, v85
	v_exp_f32_e32 v68, v68
	v_exp_f32_e32 v69, v69
	v_exp_f32_e32 v70, v70
	v_exp_f32_e32 v71, v71
	v_add_f32_e32 v68, 1.0, v68
	v_add_f32_e32 v69, 1.0, v69
	v_add_f32_e32 v70, 1.0, v70
	v_add_f32_e32 v71, 1.0, v71
	v_rcp_f32_e32 v68, v68
	v_rcp_f32_e32 v69, v69
	v_rcp_f32_e32 v70, v70
	v_rcp_f32_e32 v74, v71
	s_mov_b64 s[90:91], 0

; DEV unsigned cvtpk(float lo, float hi) { f32x2 v = {lo, hi}; bf16x2_t b = __builtin_convertvector(v, bf16x2_t); return __builtin_bit_cast(unsigned, b); }
; DEV float gelu_t(float x) { float z = 0.7978845608f * (x + 0.044715f * x * x * x); return x * __builtin_amdgcn_rcpf(1.f + __expf(-2.f * z)); }
; DEV float sigm(float x) { return __builtin_amdgcn_rcpf(1.f + __expf(-x)); }
;   __device__ __forceinline__ void operator()(const pg8::f32x4 (&acc)[2][2][4][2], const pg8::Unit& u, int wr, int wc, int fr, int fq) const {
;     ...
;       const int kind = cb < C_CQL ? 0 : ((cb < C_KR || (cb >= C_VV && cb < C_G)) ? 1 : (cb < C_Q ? 2 : (cb < C_VV ? 3 : 4)));
;       const int c0 = cb + 8 * fq;
; #pragma unroll
;       for (int ai = 0; ai < 2; ++ai)
; #pragma unroll
;         for (int m = 0; m < 4; ++m) {
;           const int row = u.pm * 256 + ai * 128 + wr * 64 + m * 16 + fr; const float rs = RS[row]; const int pos = row & seqmask;
;           u32x4 w;
; #pragma unroll
;           for (int n = 0; n < 2; ++n) {
;             pg8::f32x4 v = acc[ai][bj][m][n] * rs;
;             if (kind == 0) { v[0] = gelu_t(v[0]); v[1] = gelu_t(v[1]); v[2] = gelu_t(v[2]); v[3] = gelu_t(v[3]); }
;             else if (kind == 4) { v[0] = sigm(v[0]); v[1] = sigm(v[1]); v[2] = sigm(v[2]); v[3] = sigm(v[3]); }
;             else if (kind == 3 || kind == 2) {
;               const pg8::f32x4 cs = kind == 3 ? *(const pg8::f32x4*)(R128 + pos * 64 + ((((c0 + 4 * n) - C_Q) & 127) >> 1))
;                                               : *(const pg8::f32x4*)(R64 + pos * 32 + (((c0 + 4 * n) - C_KR) >> 1));
;               const float a0 = v[0] * cs[0] - v[1] * cs[1], a1 = v[1] * cs[0] + v[0] * cs[1], a2 = v[2] * cs[2] - v[3] * cs[3], a3 = v[3] * cs[2] + v[2] * cs[3];
;               v[0] = a0; v[1] = a1; v[2] = a2; v[3] = a3;
;             }
;             w[2 * n] = cvtpk(v[0], v[1]); w[2 * n + 1] = cvtpk(v[2], v[3]);
;           }
.LBB0_1520:
	s_and_b32 s18, s1, 6
	s_cmp_eq_u32 s18, 2
	s_cselect_b64 s[90:91], -1, 0
	s_cmp_lg_u32 s1, 3
	s_cselect_b64 s[18:19], -1, 0
	s_lshl_b32 s25, s34, 8
	v_add_u32_e32 v64, s25, v158
	v_ashrrev_i32_e32 v65, 31, v64
	v_lshl_add_u64 v[66:67], v[64:65], 2, s[12:13]
	v_mov_b32_e32 v72, v176
	s_cmp_gt_i32 s1, 3
	s_mov_b64 s[26:27], -1
	v_pk_mul_f32 v[76:77], v[62:63], v[72:73] op_sel_hi:[1,0]
	v_pk_mul_f32 v[74:75], v[60:61], v[72:73] op_sel_hi:[1,0]
	s_cbranch_scc0 .LBB0_1522
	v_mul_f32_e32 v60, 0xbfb8aa3b, v74
	v_mul_f32_e32 v61, 0xbfb8aa3b, v75
	v_mul_f32_e32 v62, 0xbfb8aa3b, v76
	v_mul_f32_e32 v63, 0xbfb8aa3b, v77
	v_exp_f32_e32 v60, v60
	v_exp_f32_e32 v61, v61
	v_exp_f32_e32 v62, v62
	v_exp_f32_e32 v63, v63
	v_add_f32_e32 v60, 1.0, v60
	v_add_f32_e32 v61, 1.0, v61
	v_add_f32_e32 v62, 1.0, v62
	v_add_f32_e32 v63, 1.0, v63
	v_rcp_f32_e32 v60, v60
	v_rcp_f32_e32 v61, v61
	v_rcp_f32_e32 v62, v62
	v_rcp_f32_e32 v66, v63
	s_mov_b64 s[26:27], 0

; DEV unsigned cvtpk(float lo, float hi) { f32x2 v = {lo, hi}; bf16x2_t b = __builtin_convertvector(v, bf16x2_t); return __builtin_bit_cast(unsigned, b); }
; DEV float gelu_t(float x) { float z = 0.7978845608f * (x + 0.044715f * x * x * x); return x * __builtin_amdgcn_rcpf(1.f + __expf(-2.f * z)); }
; DEV float sigm(float x) { return __builtin_amdgcn_rcpf(1.f + __expf(-x)); }
;   __device__ __forceinline__ void operator()(const pg8::f32x4 (&acc)[2][2][4][2], const pg8::Unit& u, int wr, int wc, int fr, int fq) const {
;     ...
;           const int row = u.pm * 256 + ai * 128 + wr * 64 + m * 16 + fr; const float rs = RS[row]; const int pos = row & seqmask;
;           u32x4 w;
; #pragma unroll
;           for (int n = 0; n < 2; ++n) {
;             pg8::f32x4 v = acc[ai][bj][m][n] * rs;
;             if (kind == 0) { v[0] = gelu_t(v[0]); v[1] = gelu_t(v[1]); v[2] = gelu_t(v[2]); v[3] = gelu_t(v[3]); }
;             else if (kind == 4) { v[0] = sigm(v[0]); v[1] = sigm(v[1]); v[2] = sigm(v[2]); v[3] = sigm(v[3]); }
;             else if (kind == 3 || kind == 2) {
;               const pg8::f32x4 cs = kind == 3 ? *(const pg8::f32x4*)(R128 + pos * 64 + ((((c0 + 4 * n) - C_Q) & 127) >> 1))
;                                               : *(const pg8::f32x4*)(R64 + pos * 32 + (((c0 + 4 * n) - C_KR) >> 1));
;               const float a0 = v[0] * cs[0] - v[1] * cs[1], a1 = v[1] * cs[0] + v[0] * cs[1], a2 = v[2] * cs[2] - v[3] * cs[3], a3 = v[3] * cs[2] + v[2] * cs[3];
;               v[0] = a0; v[1] = a1; v[2] = a2; v[3] = a3;
;             }
;             w[2 * n] = cvtpk(v[0], v[1]); w[2 * n + 1] = cvtpk(v[2], v[3]);
;           }
.LBB0_1548:
	s_nop 1
	v_add_u32_e32 v56, s25, v161
	v_ashrrev_i32_e32 v57, 31, v56
	v_lshl_add_u64 v[58:59], v[56:57], 2, s[12:13]
	v_mov_b32_e32 v64, v177
	s_cmp_gt_i32 s1, 3
	s_mov_b64 s[34:35], -1
	v_pk_mul_f32 v[68:69], v[54:55], v[64:65] op_sel_hi:[1,0]
	v_pk_mul_f32 v[66:67], v[52:53], v[64:65] op_sel_hi:[1,0]
	s_cbranch_scc0 .LBB0_1550
	v_mul_f32_e32 v52, 0xbfb8aa3b, v66
	v_mul_f32_e32 v53, 0xbfb8aa3b, v67
	v_mul_f32_e32 v54, 0xbfb8aa3b, v68
	v_mul_f32_e32 v55, 0xbfb8aa3b, v69
	v_exp_f32_e32 v52, v52
	v_exp_f32_e32 v53, v53
	v_exp_f32_e32 v54, v54
	v_exp_f32_e32 v55, v55
	v_add_f32_e32 v52, 1.0, v52
	v_add_f32_e32 v53, 1.0, v53
	v_add_f32_e32 v54, 1.0, v54
	v_add_f32_e32 v55, 1.0, v55
	v_rcp_f32_e32 v52, v52
	v_rcp_f32_e32 v53, v53
	v_rcp_f32_e32 v54, v54
	v_rcp_f32_e32 v58, v55
	s_mov_b64 s[34:35], 0

; DEV unsigned cvtpk(float lo, float hi) { f32x2 v = {lo, hi}; bf16x2_t b = __builtin_convertvector(v, bf16x2_t); return __builtin_bit_cast(unsigned, b); }
; DEV float gelu_t(float x) { float z = 0.7978845608f * (x + 0.044715f * x * x * x); return x * __builtin_amdgcn_rcpf(1.f + __expf(-2.f * z)); }
; DEV float sigm(float x) { return __builtin_amdgcn_rcpf(1.f + __expf(-x)); }
;   __device__ __forceinline__ void operator()(const pg8::f32x4 (&acc)[2][2][4][2], const pg8::Unit& u, int wr, int wc, int fr, int fq) const {
;     ...
;           const int row = u.pm * 256 + ai * 128 + wr * 64 + m * 16 + fr; const float rs = RS[row]; const int pos = row & seqmask;
;           u32x4 w;
; #pragma unroll
;           for (int n = 0; n < 2; ++n) {
;             pg8::f32x4 v = acc[ai][bj][m][n] * rs;
;             if (kind == 0) { v[0] = gelu_t(v[0]); v[1] = gelu_t(v[1]); v[2] = gelu_t(v[2]); v[3] = gelu_t(v[3]); }
;             else if (kind == 4) { v[0] = sigm(v[0]); v[1] = sigm(v[1]); v[2] = sigm(v[2]); v[3] = sigm(v[3]); }
;             else if (kind == 3 || kind == 2) {
;               const pg8::f32x4 cs = kind == 3 ? *(const pg8::f32x4*)(R128 + pos * 64 + ((((c0 + 4 * n) - C_Q) & 127) >> 1))
;                                               : *(const pg8::f32x4*)(R64 + pos * 32 + (((c0 + 4 * n) - C_KR) >> 1));
;               const float a0 = v[0] * cs[0] - v[1] * cs[1], a1 = v[1] * cs[0] + v[0] * cs[1], a2 = v[2] * cs[2] - v[3] * cs[3], a3 = v[3] * cs[2] + v[2] * cs[3];
;               v[0] = a0; v[1] = a1; v[2] = a2; v[3] = a3;
;             }
;             w[2 * n] = cvtpk(v[0], v[1]); w[2 * n + 1] = cvtpk(v[2], v[3]);
;           }
.LBB0_1576:
	s_nop 1
	v_add_u32_e32 v48, s25, v162
	v_ashrrev_i32_e32 v49, 31, v48
	v_lshl_add_u64 v[50:51], v[48:49], 2, s[12:13]
	v_mov_b32_e32 v56, v178
	s_cmp_gt_i32 s1, 3
	s_mov_b64 s[26:27], -1
	v_pk_mul_f32 v[60:61], v[46:47], v[56:57] op_sel_hi:[1,0]
	v_pk_mul_f32 v[58:59], v[44:45], v[56:57] op_sel_hi:[1,0]
	s_cbranch_scc0 .LBB0_1578
	v_mul_f32_e32 v44, 0xbfb8aa3b, v58
	v_mul_f32_e32 v45, 0xbfb8aa3b, v59
	v_mul_f32_e32 v46, 0xbfb8aa3b, v60
	v_mul_f32_e32 v47, 0xbfb8aa3b, v61
	v_exp_f32_e32 v44, v44
	v_exp_f32_e32 v45, v45
	v_exp_f32_e32 v46, v46
	v_exp_f32_e32 v47, v47
	v_add_f32_e32 v44, 1.0, v44
	v_add_f32_e32 v45, 1.0, v45
	v_add_f32_e32 v46, 1.0, v46
	v_add_f32_e32 v47, 1.0, v47
	v_rcp_f32_e32 v44, v44
	v_rcp_f32_e32 v45, v45
	v_rcp_f32_e32 v46, v46
	v_rcp_f32_e32 v50, v47
	s_mov_b64 s[26:27], 0

; DEV unsigned cvtpk(float lo, float hi) { f32x2 v = {lo, hi}; bf16x2_t b = __builtin_convertvector(v, bf16x2_t); return __builtin_bit_cast(unsigned, b); }
; DEV float gelu_t(float x) { float z = 0.7978845608f * (x + 0.044715f * x * x * x); return x * __builtin_amdgcn_rcpf(1.f + __expf(-2.f * z)); }
; DEV float sigm(float x) { return __builtin_amdgcn_rcpf(1.f + __expf(-x)); }
;   __device__ __forceinline__ void operator()(const pg8::f32x4 (&acc)[2][2][4][2], const pg8::Unit& u, int wr, int wc, int fr, int fq) const {
;     ...
;           const int row = u.pm * 256 + ai * 128 + wr * 64 + m * 16 + fr; const float rs = RS[row]; const int pos = row & seqmask;
;           u32x4 w;
; #pragma unroll
;           for (int n = 0; n < 2; ++n) {
;             pg8::f32x4 v = acc[ai][bj][m][n] * rs;
;             if (kind == 0) { v[0] = gelu_t(v[0]); v[1] = gelu_t(v[1]); v[2] = gelu_t(v[2]); v[3] = gelu_t(v[3]); }
;             else if (kind == 4) { v[0] = sigm(v[0]); v[1] = sigm(v[1]); v[2] = sigm(v[2]); v[3] = sigm(v[3]); }
;             else if (kind == 3 || kind == 2) {
;               const pg8::f32x4 cs = kind == 3 ? *(const pg8::f32x4*)(R128 + pos * 64 + ((((c0 + 4 * n) - C_Q) & 127) >> 1))
;                                               : *(const pg8::f32x4*)(R64 + pos * 32 + (((c0 + 4 * n) - C_KR) >> 1));
;               const float a0 = v[0] * cs[0] - v[1] * cs[1], a1 = v[1] * cs[0] + v[0] * cs[1], a2 = v[2] * cs[2] - v[3] * cs[3], a3 = v[3] * cs[2] + v[2] * cs[3];
;               v[0] = a0; v[1] = a1; v[2] = a2; v[3] = a3;
;             }
;             w[2 * n] = cvtpk(v[0], v[1]); w[2 * n + 1] = cvtpk(v[2], v[3]);
;           }
.LBB0_1604:
	s_nop 1
	v_add_u32_e32 v40, s25, v163
	v_ashrrev_i32_e32 v41, 31, v40
	v_lshl_add_u64 v[42:43], v[40:41], 2, s[12:13]
	v_mov_b32_e32 v48, v179
	s_cmp_gt_i32 s1, 3
	s_mov_b64 s[26:27], -1
	v_pk_mul_f32 v[52:53], v[38:39], v[48:49] op_sel_hi:[1,0]
	v_pk_mul_f32 v[50:51], v[36:37], v[48:49] op_sel_hi:[1,0]
	s_cbranch_scc0 .LBB0_1606
	v_mul_f32_e32 v36, 0xbfb8aa3b, v50
	v_mul_f32_e32 v37, 0xbfb8aa3b, v51
	v_mul_f32_e32 v38, 0xbfb8aa3b, v52
	v_mul_f32_e32 v39, 0xbfb8aa3b, v53
	v_exp_f32_e32 v36, v36
	v_exp_f32_e32 v37, v37
	v_exp_f32_e32 v38, v38
	v_exp_f32_e32 v39, v39
	v_add_f32_e32 v36, 1.0, v36
	v_add_f32_e32 v37, 1.0, v37
	v_add_f32_e32 v38, 1.0, v38
	v_add_f32_e32 v39, 1.0, v39
	v_rcp_f32_e32 v36, v36
	v_rcp_f32_e32 v37, v37
	v_rcp_f32_e32 v38, v38
	v_rcp_f32_e32 v42, v39
	s_mov_b64 s[26:27], 0

; DEV unsigned cvtpk(float lo, float hi) { f32x2 v = {lo, hi}; bf16x2_t b = __builtin_convertvector(v, bf16x2_t); return __builtin_bit_cast(unsigned, b); }
; DEV float gelu_t(float x) { float z = 0.7978845608f * (x + 0.044715f * x * x * x); return x * __builtin_amdgcn_rcpf(1.f + __expf(-2.f * z)); }
; DEV float sigm(float x) { return __builtin_amdgcn_rcpf(1.f + __expf(-x)); }
;   __device__ __forceinline__ void operator()(const pg8::f32x4 (&acc)[2][2][4][2], const pg8::Unit& u, int wr, int wc, int fr, int fq) const {
;     ...
;           const int row = u.pm * 256 + ai * 128 + wr * 64 + m * 16 + fr; const float rs = RS[row]; const int pos = row & seqmask;
;           u32x4 w;
; #pragma unroll
;           for (int n = 0; n < 2; ++n) {
;             pg8::f32x4 v = acc[ai][bj][m][n] * rs;
;             if (kind == 0) { v[0] = gelu_t(v[0]); v[1] = gelu_t(v[1]); v[2] = gelu_t(v[2]); v[3] = gelu_t(v[3]); }
;             else if (kind == 4) { v[0] = sigm(v[0]); v[1] = sigm(v[1]); v[2] = sigm(v[2]); v[3] = sigm(v[3]); }
;             else if (kind == 3 || kind == 2) {
;               const pg8::f32x4 cs = kind == 3 ? *(const pg8::f32x4*)(R128 + pos * 64 + ((((c0 + 4 * n) - C_Q) & 127) >> 1))
;                                               : *(const pg8::f32x4*)(R64 + pos * 32 + (((c0 + 4 * n) - C_KR) >> 1));
;               const float a0 = v[0] * cs[0] - v[1] * cs[1], a1 = v[1] * cs[0] + v[0] * cs[1], a2 = v[2] * cs[2] - v[3] * cs[3], a3 = v[3] * cs[2] + v[2] * cs[3];
;               v[0] = a0; v[1] = a1; v[2] = a2; v[3] = a3;
;             }
;             w[2 * n] = cvtpk(v[0], v[1]); w[2 * n + 1] = cvtpk(v[2], v[3]);
;           }
.LBB0_1632:
	s_nop 1
	v_add_u32_e32 v32, s25, v164
	v_ashrrev_i32_e32 v33, 31, v32
	v_lshl_add_u64 v[34:35], v[32:33], 2, s[12:13]
	v_mov_b32_e32 v40, v180
	s_cmp_gt_i32 s1, 3
	s_mov_b64 s[26:27], -1
	v_pk_mul_f32 v[44:45], v[30:31], v[40:41] op_sel_hi:[1,0]
	v_pk_mul_f32 v[42:43], v[28:29], v[40:41] op_sel_hi:[1,0]
	s_cbranch_scc0 .LBB0_1634
	v_mul_f32_e32 v28, 0xbfb8aa3b, v42
	v_mul_f32_e32 v29, 0xbfb8aa3b, v43
	v_mul_f32_e32 v30, 0xbfb8aa3b, v44
	v_mul_f32_e32 v31, 0xbfb8aa3b, v45
	v_exp_f32_e32 v28, v28
	v_exp_f32_e32 v29, v29
	v_exp_f32_e32 v30, v30
	v_exp_f32_e32 v31, v31
	v_add_f32_e32 v28, 1.0, v28
	v_add_f32_e32 v29, 1.0, v29
	v_add_f32_e32 v30, 1.0, v30
	v_add_f32_e32 v31, 1.0, v31
	v_rcp_f32_e32 v28, v28
	v_rcp_f32_e32 v29, v29
	v_rcp_f32_e32 v30, v30
	v_rcp_f32_e32 v34, v31
	s_mov_b64 s[26:27], 0

; DEV unsigned cvtpk(float lo, float hi) { f32x2 v = {lo, hi}; bf16x2_t b = __builtin_convertvector(v, bf16x2_t); return __builtin_bit_cast(unsigned, b); }
; DEV float gelu_t(float x) { float z = 0.7978845608f * (x + 0.044715f * x * x * x); return x * __builtin_amdgcn_rcpf(1.f + __expf(-2.f * z)); }
; DEV float sigm(float x) { return __builtin_amdgcn_rcpf(1.f + __expf(-x)); }
;   __device__ __forceinline__ void operator()(const pg8::f32x4 (&acc)[2][2][4][2], const pg8::Unit& u, int wr, int wc, int fr, int fq) const {
;     ...
;           const int row = u.pm * 256 + ai * 128 + wr * 64 + m * 16 + fr; const float rs = RS[row]; const int pos = row & seqmask;
;           u32x4 w;
; #pragma unroll
;           for (int n = 0; n < 2; ++n) {
;             pg8::f32x4 v = acc[ai][bj][m][n] * rs;
;             if (kind == 0) { v[0] = gelu_t(v[0]); v[1] = gelu_t(v[1]); v[2] = gelu_t(v[2]); v[3] = gelu_t(v[3]); }
;             else if (kind == 4) { v[0] = sigm(v[0]); v[1] = sigm(v[1]); v[2] = sigm(v[2]); v[3] = sigm(v[3]); }
;             else if (kind == 3 || kind == 2) {
;               const pg8::f32x4 cs = kind == 3 ? *(const pg8::f32x4*)(R128 + pos * 64 + ((((c0 + 4 * n) - C_Q) & 127) >> 1))
;                                               : *(const pg8::f32x4*)(R64 + pos * 32 + (((c0 + 4 * n) - C_KR) >> 1));
;               const float a0 = v[0] * cs[0] - v[1] * cs[1], a1 = v[1] * cs[0] + v[0] * cs[1], a2 = v[2] * cs[2] - v[3] * cs[3], a3 = v[3] * cs[2] + v[2] * cs[3];
;               v[0] = a0; v[1] = a1; v[2] = a2; v[3] = a3;
;             }
;             w[2 * n] = cvtpk(v[0], v[1]); w[2 * n + 1] = cvtpk(v[2], v[3]);
;           }
.LBB0_1660:
	s_nop 1
	v_add_u32_e32 v24, s25, v165
	v_ashrrev_i32_e32 v25, 31, v24
	v_lshl_add_u64 v[26:27], v[24:25], 2, s[12:13]
	v_mov_b32_e32 v32, v181
	s_cmp_gt_i32 s1, 3
	s_mov_b64 s[26:27], -1
	v_pk_mul_f32 v[36:37], v[22:23], v[32:33] op_sel_hi:[1,0]
	v_pk_mul_f32 v[34:35], v[20:21], v[32:33] op_sel_hi:[1,0]
	s_cbranch_scc0 .LBB0_1662
	v_mul_f32_e32 v20, 0xbfb8aa3b, v34
	v_mul_f32_e32 v21, 0xbfb8aa3b, v35
	v_mul_f32_e32 v22, 0xbfb8aa3b, v36
	v_mul_f32_e32 v23, 0xbfb8aa3b, v37
	v_exp_f32_e32 v20, v20
	v_exp_f32_e32 v21, v21
	v_exp_f32_e32 v22, v22
	v_exp_f32_e32 v23, v23
	v_add_f32_e32 v20, 1.0, v20
	v_add_f32_e32 v21, 1.0, v21
	v_add_f32_e32 v22, 1.0, v22
	v_add_f32_e32 v23, 1.0, v23
	v_rcp_f32_e32 v20, v20
	v_rcp_f32_e32 v21, v21
	v_rcp_f32_e32 v22, v22
	v_rcp_f32_e32 v26, v23
	s_mov_b64 s[26:27], 0

; DEV unsigned cvtpk(float lo, float hi) { f32x2 v = {lo, hi}; bf16x2_t b = __builtin_convertvector(v, bf16x2_t); return __builtin_bit_cast(unsigned, b); }
; DEV float gelu_t(float x) { float z = 0.7978845608f * (x + 0.044715f * x * x * x); return x * __builtin_amdgcn_rcpf(1.f + __expf(-2.f * z)); }
; DEV float sigm(float x) { return __builtin_amdgcn_rcpf(1.f + __expf(-x)); }
;   __device__ __forceinline__ void operator()(const pg8::f32x4 (&acc)[2][2][4][2], const pg8::Unit& u, int wr, int wc, int fr, int fq) const {
;     ...
;           const int row = u.pm * 256 + ai * 128 + wr * 64 + m * 16 + fr; const float rs = RS[row]; const int pos = row & seqmask;
;           u32x4 w;
; #pragma unroll
;           for (int n = 0; n < 2; ++n) {
;             pg8::f32x4 v = acc[ai][bj][m][n] * rs;
;             if (kind == 0) { v[0] = gelu_t(v[0]); v[1] = gelu_t(v[1]); v[2] = gelu_t(v[2]); v[3] = gelu_t(v[3]); }
;             else if (kind == 4) { v[0] = sigm(v[0]); v[1] = sigm(v[1]); v[2] = sigm(v[2]); v[3] = sigm(v[3]); }
;             else if (kind == 3 || kind == 2) {
;               const pg8::f32x4 cs = kind == 3 ? *(const pg8::f32x4*)(R128 + pos * 64 + ((((c0 + 4 * n) - C_Q) & 127) >> 1))
;                                               : *(const pg8::f32x4*)(R64 + pos * 32 + (((c0 + 4 * n) - C_KR) >> 1));
;               const float a0 = v[0] * cs[0] - v[1] * cs[1], a1 = v[1] * cs[0] + v[0] * cs[1], a2 = v[2] * cs[2] - v[3] * cs[3], a3 = v[3] * cs[2] + v[2] * cs[3];
;               v[0] = a0; v[1] = a1; v[2] = a2; v[3] = a3;
;             }
;             w[2 * n] = cvtpk(v[0], v[1]); w[2 * n + 1] = cvtpk(v[2], v[3]);
;           }
.LBB0_1688:
	s_nop 1
	v_add_u32_e32 v16, s25, v166
	v_ashrrev_i32_e32 v17, 31, v16
	v_lshl_add_u64 v[18:19], v[16:17], 2, s[12:13]
	v_mov_b32_e32 v24, v182
	s_cmp_gt_i32 s1, 3
	s_mov_b64 s[26:27], -1
	v_pk_mul_f32 v[28:29], v[14:15], v[24:25] op_sel_hi:[1,0]
	v_pk_mul_f32 v[26:27], v[12:13], v[24:25] op_sel_hi:[1,0]
	s_cbranch_scc0 .LBB0_1690
	v_mul_f32_e32 v12, 0xbfb8aa3b, v26
	v_mul_f32_e32 v13, 0xbfb8aa3b, v27
	v_mul_f32_e32 v14, 0xbfb8aa3b, v28
	v_mul_f32_e32 v15, 0xbfb8aa3b, v29
	v_exp_f32_e32 v12, v12
	v_exp_f32_e32 v13, v13
	v_exp_f32_e32 v14, v14
	v_exp_f32_e32 v15, v15
	v_add_f32_e32 v12, 1.0, v12
	v_add_f32_e32 v13, 1.0, v13
	v_add_f32_e32 v14, 1.0, v14
	v_add_f32_e32 v15, 1.0, v15
	v_rcp_f32_e32 v12, v12
	v_rcp_f32_e32 v13, v13
	v_rcp_f32_e32 v14, v14
	v_rcp_f32_e32 v18, v15
	s_mov_b64 s[26:27], 0

; DEV unsigned cvtpk(float lo, float hi) { f32x2 v = {lo, hi}; bf16x2_t b = __builtin_convertvector(v, bf16x2_t); return __builtin_bit_cast(unsigned, b); }
; DEV float gelu_t(float x) { float z = 0.7978845608f * (x + 0.044715f * x * x * x); return x * __builtin_amdgcn_rcpf(1.f + __expf(-2.f * z)); }
; DEV float sigm(float x) { return __builtin_amdgcn_rcpf(1.f + __expf(-x)); }
;   __device__ __forceinline__ void operator()(const pg8::f32x4 (&acc)[2][2][4][2], const pg8::Unit& u, int wr, int wc, int fr, int fq) const {
;     ...
;           const int row = u.pm * 256 + ai * 128 + wr * 64 + m * 16 + fr; const float rs = RS[row]; const int pos = row & seqmask;
;           u32x4 w;
; #pragma unroll
;           for (int n = 0; n < 2; ++n) {
;             pg8::f32x4 v = acc[ai][bj][m][n] * rs;
;             if (kind == 0) { v[0] = gelu_t(v[0]); v[1] = gelu_t(v[1]); v[2] = gelu_t(v[2]); v[3] = gelu_t(v[3]); }
;             else if (kind == 4) { v[0] = sigm(v[0]); v[1] = sigm(v[1]); v[2] = sigm(v[2]); v[3] = sigm(v[3]); }
;             else if (kind == 3 || kind == 2) {
;               const pg8::f32x4 cs = kind == 3 ? *(const pg8::f32x4*)(R128 + pos * 64 + ((((c0 + 4 * n) - C_Q) & 127) >> 1))
;                                               : *(const pg8::f32x4*)(R64 + pos * 32 + (((c0 + 4 * n) - C_KR) >> 1));
;               const float a0 = v[0] * cs[0] - v[1] * cs[1], a1 = v[1] * cs[0] + v[0] * cs[1], a2 = v[2] * cs[2] - v[3] * cs[3], a3 = v[3] * cs[2] + v[2] * cs[3];
;               v[0] = a0; v[1] = a1; v[2] = a2; v[3] = a3;
;             }
;             w[2 * n] = cvtpk(v[0], v[1]); w[2 * n + 1] = cvtpk(v[2], v[3]);
;           }
.LBB0_1716:
	s_nop 1
	v_add_u32_e32 v8, s25, v167
	v_ashrrev_i32_e32 v9, 31, v8
	v_lshl_add_u64 v[10:11], v[8:9], 2, s[12:13]
	v_mov_b32_e32 v16, v183
	s_cmp_gt_i32 s1, 3
	s_mov_b64 s[26:27], -1
	v_pk_mul_f32 v[20:21], v[6:7], v[16:17] op_sel_hi:[1,0]
	v_pk_mul_f32 v[18:19], v[4:5], v[16:17] op_sel_hi:[1,0]
	s_cbranch_scc0 .LBB0_1718
	v_mul_f32_e32 v4, 0xbfb8aa3b, v18
	v_mul_f32_e32 v5, 0xbfb8aa3b, v19
	v_mul_f32_e32 v6, 0xbfb8aa3b, v20
	v_mul_f32_e32 v7, 0xbfb8aa3b, v21
	v_exp_f32_e32 v4, v4
	v_exp_f32_e32 v5, v5
	v_exp_f32_e32 v6, v6
	v_exp_f32_e32 v7, v7
	v_add_f32_e32 v4, 1.0, v4
	v_add_f32_e32 v5, 1.0, v5
	v_add_f32_e32 v6, 1.0, v6
	v_add_f32_e32 v7, 1.0, v7
	v_rcp_f32_e32 v4, v4
	v_rcp_f32_e32 v5, v5
	v_rcp_f32_e32 v6, v6
	v_rcp_f32_e32 v10, v7
	s_mov_b64 s[26:27], 0
